# v7 + one static s_setprio 1 for the lagging half (waves 4-7) per GEMM phase
# speedup vs baseline: 1.0044x; 1.0044x over previous
.LBB0_95:
	v_readlane_b32 s4, v251, 8
	s_cmp_lt_i32 s4, 2
	v_readlane_b32 s5, v251, 9
	s_cselect_b64 s[0:1], -1, 0
	s_add_u32 s4, s94, 0x27800000
	s_addc_u32 s5, s95, 0
	s_add_u32 s84, s94, 0x27c00000
	v_readlane_b32 s6, v251, 10
	v_readlane_b32 s7, v251, 11
	v_writelane_b32 v251, s4, 42
	s_addc_u32 s85, s95, 0
	v_mov_b32_e32 v1, v0
	v_writelane_b32 v251, s5, 43
	s_add_u32 s4, s94, 0x38000000
	v_writelane_b32 v251, s4, 44
	s_addc_u32 s4, s95, 0
	s_ashr_i32 s78, s81, 31
	v_writelane_b32 v251, s4, 45
	s_lshr_b32 s4, s78, 29
	s_add_i32 s4, s81, s4
	s_ashr_i32 s5, s4, 3
	s_and_b32 s4, s4, -8
	s_and_b64 s[2:3], s[0:1], s[2:3]
	s_sub_i32 s4, s81, s4
	v_writelane_b32 v251, s5, 46
	s_cmp_lt_i32 s4, 0
	v_writelane_b32 v251, s4, 47
	s_cselect_b64 s[4:5], -1, 0
	v_writelane_b32 v251, s4, 48
	s_ashr_i32 s79, s82, 31
	s_andn2_b64 vcc, exec, s[2:3]
	v_writelane_b32 v251, s5, 49
	s_cbranch_vccnz .LBB0_125
	v_mov_b32_e32 v4, v0
	s_cmpk_gt_i32 s81, 0x3ff
	s_nop 0
	v_readfirstlane_b32 s3, v4
	s_cbranch_scc1 .LBB0_125
	v_lshlrev_b32_e32 v1, 4, v4
	v_add_u32_e32 v3, 0x2000, v1
	v_ashrrev_i32_e32 v2, 31, v3
	v_lshrrev_b32_e32 v2, 22, v2
	v_add_u32_e32 v2, v3, v2
	v_ashrrev_i32_e32 v2, 10, v2
	v_mul_i32_i24_e32 v5, 0x400, v2
	v_sub_u32_e32 v3, v3, v5
	v_lshrrev_b32_e32 v5, 4, v3
	v_bitop3_b32 v5, v5, v3, 32 bitop3:0x6c
	v_ashrrev_i32_e32 v3, 31, v5
	v_lshrrev_b32_e32 v3, 26, v3
	s_waitcnt vmcnt(10)
	v_add_u32_e32 v6, v5, v3
	v_lshlrev_b32_e32 v7, 3, v2
	v_ashrrev_i32_e32 v3, 6, v6
	v_and_b32_e32 v7, -16, v7
	v_readlane_b32 s4, v251, 47
	v_add_u32_e32 v7, v3, v7
	s_lshl_b32 s2, s4, 7
	s_mul_i32 s6, s4, 0x81
	v_and_b32_e32 v8, 3, v3
	s_mov_b32 s4, 0x1ffffe0
	v_lshrrev_b32_e32 v9, 2, v7
	s_waitcnt vmcnt(9)
	v_lshlrev_b32_e32 v10, 1, v7
	v_and_or_b32 v8, v7, s4, v8
	v_and_b32_e32 v9, 4, v9
	v_and_b32_e32 v10, 24, v10
	v_and_b32_e32 v6, 0xc0, v6
	v_or3_b32 v8, v8, v9, v10
	v_sub_u32_e32 v5, v5, v6
	v_mov_b32_e32 v10, 1
	v_lshlrev_b32_e32 v9, 5, v2
	v_ashrrev_i16_sdwa v5, v10, sext(v5) dst_sel:DWORD dst_unused:UNUSED_PAD src0_sel:DWORD src1_sel:BYTE_0
	v_and_b32_e32 v9, 32, v9
	v_bfe_i32 v5, v5, 0, 16
	v_add_lshl_u32 v6, v9, v5, 1
	v_lshl_add_u32 v134, v8, 7, v6
	v_lshl_add_u32 v136, v7, 7, v6
	v_bfe_i32 v6, v4, 27, 1
	v_lshrrev_b32_e32 v6, 22, v6
	v_add_u32_e32 v6, v1, v6
	v_and_b32_e32 v6, 0xfffffc00, v6
	v_sub_u32_e32 v1, v1, v6
	v_lshrrev_b32_e32 v6, 4, v1
	v_bitop3_b32 v8, v6, v1, 32 bitop3:0x6c
	v_ashrrev_i32_e32 v1, 31, v1
	v_lshrrev_b32_e32 v1, 26, v1
	v_add_u32_e32 v1, v8, v1
	v_ashrrev_i32_e32 v6, 6, v1
	v_ashrrev_i32_e32 v1, 31, v4
	v_lshrrev_b32_e32 v1, 26, v1
	v_add_u32_e32 v1, v4, v1
	v_ashrrev_i32_e32 v7, 6, v1
	v_lshlrev_b32_e32 v1, 3, v7
	v_and_b32_e32 v1, -16, v1
	v_add_u32_e32 v1, v6, v1
	v_and_b32_e32 v9, 3, v6
	s_ashr_i32 s9, s3, 6
	v_and_or_b32 v9, v1, s4, v9
	v_readlane_b32 s4, v251, 48
	s_ashr_i32 s8, s3, 8
	s_lshl_b32 s28, s9, 10
	v_readlane_b32 s5, v251, 49
	s_and_b64 s[4:5], s[4:5], exec
	s_cselect_b32 s2, s6, s2
	v_readlane_b32 s4, v251, 46
	s_add_i32 s2, s2, s4
	s_ashr_i32 s4, s2, 31
	s_lshr_b32 s4, s4, 25
	s_add_i32 s4, s2, s4
	s_ashr_i32 s5, s4, 7
	s_and_b32 s4, s4, 0xff80
	s_sub_i32 s4, s2, s4
	s_bfe_i32 s2, s4, 0x80000
	s_bfe_u32 s2, s2, 0x2000d
	s_add_i32 s6, s4, s2
	s_bfe_i32 s2, s6, 0x80000
	s_and_b32 s6, s6, 0xfc
	v_lshrrev_b32_e32 v11, 2, v1
	v_lshlrev_b32_e32 v12, 1, v1
	s_sub_i32 s4, s4, s6
	v_and_b32_e32 v11, 4, v11
	v_and_b32_e32 v12, 24, v12
	s_lshl_b32 s5, s5, 2
	s_sext_i32_i16 s2, s2
	s_sext_i32_i8 s4, s4
	v_or3_b32 v9, v9, v11, v12
	v_mul_i32_i24_e32 v12, 64, v6
	s_lshr_b32 s2, s2, 2
	s_add_i32 s4, s5, s4
	v_sub_u32_e32 v8, v8, v12
	s_ashr_i32 s5, s4, 31
	s_bfe_i64 s[10:11], s[2:3], 0x100000
	v_lshlrev_b32_e32 v11, 5, v7
	v_ashrrev_i16_sdwa v8, v10, sext(v8) dst_sel:DWORD dst_unused:UNUSED_PAD src0_sel:DWORD src1_sel:BYTE_0
	s_lshl_b64 s[6:7], s[4:5], 21
	s_lshl_b64 s[10:11], s[10:11], 21
	v_and_b32_e32 v11, 32, v11
	v_bfe_i32 v8, v8, 0, 16
	s_add_u32 s22, s76, s10
	v_add_lshl_u32 v10, v11, v8, 1
	s_addc_u32 s23, s77, s11
	s_add_i32 s29, s28, 0
	v_lshl_add_u32 v138, v9, 7, v10
	s_add_i32 m0, s29, 0x10000
	v_lshl_add_u32 v140, v1, 7, v10
	global_load_lds_dwordx4 v138, s[22:23]
	s_add_i32 m0, s29, 0x12000
	s_add_u32 s10, s22, 0x100000
	global_load_lds_dwordx4 v134, s[22:23]
	s_addc_u32 s11, s23, 0
	s_add_i32 m0, s29, 0x14000
	v_mov_b32_e32 v139, 0
	global_load_lds_dwordx4 v138, s[10:11]
	s_add_i32 m0, s29, 0x16000
	s_mov_b32 s5, 0
	global_load_lds_dwordx4 v134, s[10:11]
	v_readlane_b32 s10, v251, 17
	v_readlane_b32 s11, v251, 18
	s_add_u32 s20, s10, s6
	s_addc_u32 s21, s11, s7
	s_add_i32 s30, s29, 0x2000
	s_mov_b32 m0, s29
	s_add_u32 s6, s20, 0x100000
	global_load_lds_dwordx4 v140, s[20:21]
	s_mov_b32 m0, s30
	s_addc_u32 s7, s21, 0
	s_add_i32 s31, s29, 0x4000
	global_load_lds_dwordx4 v136, s[20:21]
	s_mov_b32 m0, s31
	s_add_i32 s33, s29, 0x6000
	global_load_lds_dwordx4 v140, s[6:7]
	s_mov_b32 m0, s33
	s_cmp_eq_u32 s8, 1
	global_load_lds_dwordx4 v136, s[6:7]
	v_mov_b32_e32 v135, v139
	v_mov_b32_e32 v141, v139
	s_cselect_b64 s[6:7], -1, 0
	s_cmp_lg_u32 s8, 1
	v_mov_b32_e32 v137, v139
	s_cbranch_scc1 .LBB0_99
	s_barrier
	s_setprio 1

.LBB0_179:
	s_setprio 0
	v_readlane_b32 s4, v251, 8
	s_cmp_lt_i32 s4, 3
	s_cselect_b64 s[8:9], -1, 0
	s_add_u32 s0, s94, 0x27900000
	s_addc_u32 s1, s95, 0
	v_readlane_b32 s5, v251, 9
	v_readlane_b32 s6, v251, 10
	v_readlane_b32 s7, v251, 11
	v_writelane_b32 v251, s0, 50
	s_mul_i32 s7, s50, 0x4600
	v_mov_b32_e32 v2, v0
	v_writelane_b32 v251, s1, 51
	s_add_u32 s0, s94, 0x27980000
	s_addc_u32 s1, s95, 0
	s_add_u32 s86, s94, 0x4a300000
	v_writelane_b32 v251, s0, 52
	s_addc_u32 s83, s95, 0
	s_add_u32 s33, s94, 0x4e300000
	v_writelane_b32 v251, s1, 53
	s_addc_u32 s4, s95, 0
	v_writelane_b32 v251, s8, 54
	s_add_u32 s5, s94, 0x50300000
	s_addc_u32 s6, s95, 0
	v_writelane_b32 v251, s9, 55
	s_and_b64 s[0:1], s[8:9], s[2:3]
	v_writelane_b32 v251, s81, 56
	s_add_i32 s87, s7, 0
	s_andn2_b64 vcc, exec, s[0:1]
	v_writelane_b32 v251, s78, 57
	v_writelane_b32 v251, s79, 58
	s_cbranch_vccnz .LBB0_280
	s_cmpk_gt_i32 s90, 0x7ff
	s_cbranch_scc1 .LBB0_280
	v_mbcnt_lo_u32_b32 v3, -1, 0
	v_mbcnt_hi_u32_b32 v3, -1, v3
	v_and_b32_e32 v4, 64, v3
	v_bfrev_b32_e32 v5, 0.5
	v_lshl_or_b32 v178, v3, 2, v5
	v_xor_b32_e32 v5, 1, v3
	s_waitcnt vmcnt(0)
	v_add_u32_e32 v6, 64, v4
	v_cmp_lt_i32_e32 vcc, v5, v6
	v_bfe_u32 v176, v2, 4, 2
	v_lshlrev_b32_e32 v9, 3, v176
	v_cndmask_b32_e32 v5, v3, v5, vcc
	v_lshlrev_b32_e32 v183, 2, v5
	v_xor_b32_e32 v5, 2, v3
	v_cmp_lt_i32_e32 vcc, v5, v6
	v_bfe_u32 v11, v2, 2, 2
	v_and_b32_e32 v10, 8, v9
	v_cndmask_b32_e32 v5, v3, v5, vcc
	v_or_b32_e32 v189, v11, v9
	v_lshlrev_b32_e32 v9, 2, v176
	v_lshlrev_b32_e32 v184, 2, v5
	v_xor_b32_e32 v5, 4, v3
	v_and_b32_e32 v12, 4, v9
	v_cmp_lt_i32_e32 vcc, v5, v6
	v_or_b32_e32 v12, v12, v11
	v_lshlrev_b32_e32 v190, 5, v12
	v_cndmask_b32_e32 v5, v3, v5, vcc
	v_lshlrev_b32_e32 v12, 3, v2
	v_lshlrev_b32_e32 v185, 2, v5
	v_xor_b32_e32 v5, 8, v3
	v_and_b32_e32 v13, 8, v12
	v_cmp_lt_i32_e32 vcc, v5, v6
	v_add_u32_e32 v191, s87, v13
	v_add_u32_e32 v13, -1, v3
	v_cndmask_b32_e32 v5, v3, v5, vcc
	v_cmp_lt_i32_e32 vcc, v13, v4
	v_lshlrev_b32_e32 v186, 2, v5
	v_lshlrev_b32_e32 v5, 1, v2
	v_cndmask_b32_e32 v13, v13, v3, vcc
	v_lshlrev_b32_e32 v194, 2, v13
	v_add_u32_e32 v13, -2, v3
	v_cmp_lt_i32_e32 vcc, v13, v4
	v_and_b32_e32 v7, 8, v2
	v_bfe_u32 v8, v2, 5, 1
	v_cndmask_b32_e32 v13, v13, v3, vcc
	v_lshlrev_b32_e32 v195, 2, v13
	v_add_u32_e32 v13, -4, v3
	v_cmp_lt_i32_e32 vcc, v13, v4
	v_and_b32_e32 v6, 14, v5
	v_bitop3_b32 v5, v5, v7, 14 bitop3:0x6c
	v_cndmask_b32_e32 v13, v13, v3, vcc
	v_lshlrev_b32_e32 v196, 2, v13
	v_add_u32_e32 v13, -8, v3
	v_cmp_lt_i32_e32 vcc, v13, v4
	v_and_b32_e32 v177, 15, v2
	v_or_b32_e32 v193, v9, v11
	v_cndmask_b32_e32 v13, v13, v3, vcc
	v_lshlrev_b32_e32 v197, 2, v13
	v_add_u32_e32 v13, -16, v3
	v_cmp_lt_i32_e32 vcc, v13, v4
	v_writelane_b32 v251, s50, 59
	s_add_u32 s0, s94, 0x27a00000
	v_cndmask_b32_e32 v13, v13, v3, vcc
	v_lshlrev_b32_e32 v198, 2, v13
	v_subrev_u32_e32 v13, 32, v3
	v_cmp_lt_i32_e32 vcc, v13, v4
	v_xor_b32_e32 v4, v176, v5
	v_and_b32_e32 v1, 63, v2
	v_cndmask_b32_e32 v3, v13, v3, vcc
	v_lshlrev_b32_e32 v199, 2, v3
	v_or_b32_e32 v3, 2, v8
	v_xor_b32_e32 v3, v3, v5
	v_lshlrev_b32_e32 v13, 4, v3
	v_or_b32_e32 v3, 4, v176
	v_xor_b32_e32 v14, v3, v5
	v_or_b32_e32 v3, 4, v8
	v_xor_b32_e32 v3, v3, v5
	v_lshlrev_b32_e32 v15, 4, v3
	v_or_b32_e32 v3, 6, v8
	v_xor_b32_e32 v3, v3, v5
	v_lshlrev_b32_e32 v16, 4, v3
	v_or_b32_e32 v3, 8, v176
	v_xor_b32_e32 v17, v3, v5
	v_or_b32_e32 v3, 8, v8
	v_xor_b32_e32 v3, v3, v5
	v_lshlrev_b32_e32 v18, 4, v3
	v_or_b32_e32 v3, 10, v8
	v_xor_b32_e32 v3, v3, v5
	v_lshlrev_b32_e32 v19, 4, v3
	v_or_b32_e32 v3, 12, v176
	v_xor_b32_e32 v20, v3, v5
	v_or_b32_e32 v3, 12, v8
	v_xor_b32_e32 v3, v3, v5
	v_lshlrev_b32_e32 v21, 4, v3
	v_or_b32_e32 v3, 14, v8
	v_xor_b32_e32 v3, v3, v5
	v_lshlrev_b32_e32 v5, 4, v3
	v_bitop3_b32 v3, v11, v9, 4 bitop3:0x72
	v_lshlrev_b32_e32 v9, 8, v177
	v_lshl_or_b32 v4, v4, 4, v9
	v_add_u32_e32 v202, 0, v4
	v_bitop3_b32 v4, v6, v8, v7 bitop3:0xde
	v_writelane_b32 v251, s0, 60
	s_addc_u32 s0, s95, 0
	v_lshlrev_b32_e32 v4, 4, v4
	v_writelane_b32 v251, s0, 61
	v_cmp_gt_u32_e64 s[0:1], 2, v1
	v_or3_b32 v4, v9, v4, v10
	v_add_u32_e32 v203, 0, v4
	v_writelane_b32 v251, s0, 62
	v_lshl_add_u32 v4, v177, 2, 0
	v_add_u32_e32 v204, 0x4000, v4
	v_writelane_b32 v251, s1, 63
	v_cmp_gt_u32_e64 s[0:1], 4, v1
	v_lshl_or_b32 v4, v20, 4, v9
	v_add_u32_e32 v205, 0, v4
	v_writelane_b32 v250, s0, 0
	v_lshl_or_b32 v4, v14, 4, v9
	v_add_u32_e32 v206, 0, v4
	v_writelane_b32 v250, s1, 1
	v_cmp_gt_u32_e64 s[0:1], 8, v1
	v_lshl_or_b32 v4, v17, 4, v9
	v_add_u32_e32 v207, 0, v4
	v_writelane_b32 v250, s0, 2
	v_or3_b32 v4, v9, v13, v10
	v_add_u32_e32 v208, 0, v4
	v_writelane_b32 v250, s1, 3
	v_cmp_gt_u32_e64 s[0:1], 16, v1
	v_or3_b32 v4, v9, v16, v10
	v_and_b32_e32 v181, 48, v2
	v_lshrrev_b32_e32 v2, 3, v2
	v_writelane_b32 v250, s0, 4
	v_add_u32_e32 v209, 0, v4
	v_or3_b32 v4, v9, v19, v10
	v_mov_b32_e32 v113, 0
	v_and_b32_e32 v2, 4, v2
	v_writelane_b32 v250, s1, 5
	v_cmp_gt_u32_e64 s[0:1], 32, v1
	v_add_u32_e32 v210, 0, v4
	v_or3_b32 v4, v9, v5, v10
	v_lshlrev_b32_e32 v110, 4, v1
	v_mov_b32_e32 v111, v113
	v_writelane_b32 v250, s0, 6
	v_bitop3_b32 v2, v193, v2, 7 bitop3:0x6c
	v_add_u32_e32 v211, 0, v4
	v_or3_b32 v4, v9, v21, v10
	v_writelane_b32 v250, s1, 7
	v_lshlrev_b32_e32 v200, 5, v3
	v_lshlrev_b32_e32 v201, 5, v2
	v_lshl_add_u64 v[2:3], s[94:95], 0, v[110:111]
	s_mov_b64 s[0:1], 0x52304800
	v_add_u32_e32 v212, 0, v4
	v_or3_b32 v4, v9, v18, v10
	s_add_u32 s8, s94, 0x4c300000
	v_lshlrev_b32_e32 v187, 3, v1
	v_lshl_add_u32 v188, v176, 5, s87
	v_lshl_add_u64 v[114:115], v[2:3], 0, s[0:1]
	v_add_u32_e32 v213, 0, v4
	v_or3_b32 v4, v9, v15, v10
	s_mov_b64 s[0:1], 0x52308800
	s_addc_u32 s9, s95, 0
	s_mov_b32 s81, 0
	v_lshl_add_u32 v179, v1, 2, s87
	v_cmp_eq_u32_e64 s[2:3], 0, v1
	v_lshlrev_b32_e32 v180, 3, v177
	v_add_u32_e32 v182, -3, v181
	v_sub_u32_e32 v192, v188, v181
	v_add_u32_e32 v214, 0, v4
	v_and_b32_e32 v215, 16, v12
	v_or_b32_e32 v216, 0x400, v187
	v_lshl_add_u64 v[116:117], v[2:3], 0, s[0:1]
	v_mov_b32_e32 v217, 0x3ecc95a3
	s_mov_b32 s10, 0x3fb8aa3b
	s_mov_b32 s11, 0xc2ce8ed0
	s_mov_b32 s12, 0x42b17218
	s_mov_b32 s13, 0x8200
	s_mov_b32 s78, 0xf800000
	v_mov_b32_e32 v218, 0x260
	v_mov_b32_e32 v219, 0x7f800000
	v_mov_b32_e32 v220, 0xe000
	s_mov_b32 s79, s90
	s_branch .LBB0_183

.LBB0_365:
	v_readlane_b32 s4, v251, 8
	s_cmp_lt_i32 s4, 5
	s_cselect_b64 s[0:1], -1, 0
	s_add_u32 s8, s94, 0xd000000
	s_addc_u32 s9, s95, 0
	s_add_u32 s52, s94, 0xea00000
	s_addc_u32 s53, s95, 0
	s_add_u32 s65, s94, 0x10b00000
	s_addc_u32 s4, s95, 0
	s_add_u32 s51, s94, 0x18d00000
	v_readlane_b32 s5, v251, 9
	v_readlane_b32 s6, v251, 10
	v_readlane_b32 s7, v251, 11
	v_writelane_b32 v251, s4, 50
	s_addc_u32 s4, s95, 0
	s_add_u32 s48, s94, 0x20e00000
	v_writelane_b32 v251, s4, 62
	s_addc_u32 s49, s95, 0
	s_add_u32 s54, s94, 0x22f00000
	v_readlane_b32 s12, v251, 26
	s_addc_u32 s55, s95, 0
	s_and_b64 s[2:3], s[0:1], s[2:3]
	s_and_b32 s33, s81, 7
	v_readlane_b32 s26, v251, 40
	v_readlane_b32 s27, v251, 41
	s_cmp_lg_u64 s[26:27], 0
	s_cselect_b64 s[4:5], -1, 0
	v_mov_b32_e32 v156, v0
	s_andn2_b64 vcc, exec, s[2:3]
	v_readlane_b32 s13, v251, 27
	v_readlane_b32 s14, v251, 28
	v_readlane_b32 s15, v251, 29
	v_readlane_b32 s16, v251, 30
	v_readlane_b32 s17, v251, 31
	v_readlane_b32 s18, v251, 32
	v_readlane_b32 s19, v251, 33
	v_readlane_b32 s20, v251, 34
	v_readlane_b32 s21, v251, 35
	v_readlane_b32 s22, v251, 36
	v_readlane_b32 s23, v251, 37
	v_readlane_b32 s24, v251, 38
	v_readlane_b32 s25, v251, 39
	v_writelane_b32 v250, s65, 0
	s_cbranch_vccnz .LBB0_472
	s_cmp_gt_i32 s81, 63
	s_mov_b64 s[2:3], -1
	s_cbranch_scc0 .LBB0_393
	s_sub_i32 s40, s81, 64
	v_mov_b32_e32 v4, v0
	s_cmpk_gt_u32 s40, 0x5ff
	s_nop 0
	v_readfirstlane_b32 s2, v4
	s_cbranch_scc1 .LBB0_392
	v_lshlrev_b32_e32 v1, 4, v4
	v_add_u32_e32 v3, 0x2000, v1
	v_ashrrev_i32_e32 v2, 31, v3
	v_lshrrev_b32_e32 v2, 22, v2
	v_add_u32_e32 v2, v3, v2
	v_ashrrev_i32_e32 v2, 10, v2
	v_mul_i32_i24_e32 v5, 0x400, v2
	s_ashr_i32 s12, s2, 6
	v_sub_u32_e32 v3, v3, v5
	s_ashr_i32 s3, s2, 8
	s_lshl_b32 s41, s12, 10
	v_lshrrev_b32_e32 v5, 4, v3
	s_add_u32 s42, s94, 0x4200000
	v_bitop3_b32 v5, v5, v3, 32 bitop3:0x6c
	s_addc_u32 s43, s95, 0
	s_lshr_b32 s6, s40, 3
	s_mul_i32 s7, s33, 0xc0
	v_ashrrev_i32_e32 v3, 31, v5
	s_add_i32 s6, s7, s6
	v_lshrrev_b32_e32 v3, 26, v3
	s_mul_i32 s7, s6, 0xaaab
	s_waitcnt vmcnt(0)
	v_add_u32_e32 v6, v5, v3
	v_lshlrev_b32_e32 v7, 3, v2
	s_lshr_b32 s7, s7, 23
	v_ashrrev_i32_e32 v3, 6, v6
	v_and_b32_e32 v7, -16, v7
	s_lshl_b32 s10, s7, 2
	s_mulk_i32 s7, 0xc0
	v_add_u32_e32 v7, v3, v7
	s_sub_i32 s6, s6, s7
	v_and_b32_e32 v8, 3, v3
	s_mov_b32 s7, 0x1ffffe0
	v_lshrrev_b32_e32 v9, 2, v7
	v_lshlrev_b32_e32 v10, 1, v7
	v_and_or_b32 v8, v7, s7, v8
	v_and_b32_e32 v9, 4, v9
	v_and_b32_e32 v10, 24, v10
	v_and_b32_e32 v6, 0xc0, v6
	v_or3_b32 v8, v8, v9, v10
	v_sub_u32_e32 v5, v5, v6
	v_mov_b32_e32 v10, 1
	v_lshlrev_b32_e32 v9, 5, v2
	v_ashrrev_i16_sdwa v5, v10, sext(v5) dst_sel:DWORD dst_unused:UNUSED_PAD src0_sel:DWORD src1_sel:BYTE_0
	v_and_b32_e32 v9, 32, v9
	v_bfe_i32 v5, v5, 0, 16
	v_add_lshl_u32 v6, v9, v5, 1
	v_lshl_add_u32 v134, v8, 7, v6
	v_lshl_add_u32 v136, v7, 7, v6
	v_bfe_i32 v6, v4, 27, 1
	v_lshrrev_b32_e32 v6, 22, v6
	v_add_u32_e32 v6, v1, v6
	v_and_b32_e32 v6, 0xfffffc00, v6
	v_sub_u32_e32 v1, v1, v6
	v_lshrrev_b32_e32 v6, 4, v1
	v_bitop3_b32 v8, v6, v1, 32 bitop3:0x6c
	v_ashrrev_i32_e32 v1, 31, v1
	v_lshrrev_b32_e32 v1, 26, v1
	v_add_u32_e32 v1, v8, v1
	v_ashrrev_i32_e32 v6, 6, v1
	v_ashrrev_i32_e32 v1, 31, v4
	v_lshrrev_b32_e32 v1, 26, v1
	v_add_u32_e32 v1, v4, v1
	v_ashrrev_i32_e32 v7, 6, v1
	v_lshlrev_b32_e32 v1, 3, v7
	v_and_b32_e32 v1, -16, v1
	v_add_u32_e32 v1, v6, v1
	v_and_b32_e32 v9, 3, v6
	v_lshrrev_b32_e32 v11, 2, v1
	v_lshlrev_b32_e32 v12, 1, v1
	v_and_or_b32 v9, v1, s7, v9
	v_and_b32_e32 v11, 4, v11
	v_and_b32_e32 v12, 24, v12
	v_or3_b32 v9, v9, v11, v12
	v_mul_i32_i24_e32 v12, 64, v6
	v_sub_u32_e32 v8, v8, v12
	s_and_b32 s13, s10, 0xfffc
	v_lshlrev_b32_e32 v11, 5, v7
	v_ashrrev_i16_sdwa v8, v10, sext(v8) dst_sel:DWORD dst_unused:UNUSED_PAD src0_sel:DWORD src1_sel:BYTE_0
	s_sub_i32 s10, 32, s13
	v_and_b32_e32 v11, 32, v11
	v_bfe_i32 v8, v8, 0, 16
	s_min_u32 s14, s10, 4
	v_add_lshl_u32 v10, v11, v8, 1
	v_lshl_add_u32 v138, v9, 7, v10
	v_cvt_f32_ubyte0_e32 v9, s14
	v_lshl_add_u32 v140, v1, 7, v10
	v_rcp_iflag_f32_e32 v10, v9
	v_cvt_f32_ubyte0_e32 v1, s6
	s_mov_b32 s7, 0
	v_mov_b32_e32 v139, 0
	v_mul_f32_e32 v10, v1, v10
	v_trunc_f32_e32 v10, v10
	v_fma_f32 v1, -v10, v9, v1
	v_cvt_u32_f32_e32 v10, v10
	v_cmp_ge_f32_e64 s[10:11], |v1|, v9
	s_cmp_lg_u64 s[10:11], 0
	v_mov_b32_e32 v135, v139
	v_readfirstlane_b32 s15, v10
	s_addc_u32 s15, s15, 0
	s_mul_i32 s10, s15, s14
	s_sub_i32 s6, s6, s10
	s_and_b32 s6, s6, 0xff
	s_add_i32 s6, s6, s13
	s_and_b32 s79, s15, 0xff
	s_lshl_b64 s[10:11], s[6:7], 21
	s_lshl_b32 s13, s79, 21
	s_add_u32 s34, s42, s13
	s_addc_u32 s35, s43, 0
	s_add_i32 s46, s41, 0
	s_add_i32 m0, s46, 0x10000
	v_mov_b32_e32 v141, v139
	global_load_lds_dwordx4 v138, s[34:35]
	s_add_i32 m0, s46, 0x12000
	s_add_u32 s14, s34, 0x100000
	global_load_lds_dwordx4 v134, s[34:35]
	s_addc_u32 s15, s35, 0
	s_add_i32 m0, s46, 0x14000
	v_mov_b32_e32 v137, v139
	global_load_lds_dwordx4 v138, s[14:15]
	s_add_i32 m0, s46, 0x16000
	s_nop 0
	global_load_lds_dwordx4 v134, s[14:15]
	v_readlane_b32 s14, v251, 17
	v_readlane_b32 s15, v251, 18
	s_add_u32 s26, s14, s10
	s_addc_u32 s27, s15, s11
	s_add_i32 s47, s46, 0x2000
	s_mov_b32 m0, s46
	s_add_u32 s10, s26, 0x100000
	global_load_lds_dwordx4 v140, s[26:27]
	s_mov_b32 m0, s47
	s_addc_u32 s11, s27, 0
	s_add_i32 s58, s46, 0x4000
	global_load_lds_dwordx4 v136, s[26:27]
	s_mov_b32 m0, s58
	s_add_i32 s59, s46, 0x6000
	global_load_lds_dwordx4 v140, s[10:11]
	s_mov_b32 m0, s59
	s_cmp_eq_u32 s3, 1
	global_load_lds_dwordx4 v136, s[10:11]
	s_cselect_b64 s[10:11], -1, 0
	s_cmp_lg_u32 s3, 1
	s_cbranch_scc1 .LBB0_370
	s_barrier
	s_setprio 1

.LBB0_526:
	s_setprio 0
	v_readlane_b32 s12, v251, 8
	s_cmp_lt_i32 s12, 6
	s_cselect_b64 s[0:1], -1, 0
	s_and_b64 s[2:3], s[0:1], s[2:3]
	v_mov_b32_e32 v1, v0
	s_andn2_b64 vcc, exec, s[2:3]
	v_readlane_b32 s13, v251, 9
	v_readlane_b32 s14, v251, 10
	v_readlane_b32 s15, v251, 11
	s_cbranch_vccnz .LBB0_622
	v_mov_b32_e32 v4, v0
	s_cmpk_gt_i32 s81, 0x29f
	s_nop 0
	v_readfirstlane_b32 s3, v4
	s_cbranch_scc1 .LBB0_552
	s_waitcnt vmcnt(0)
	v_lshlrev_b32_e32 v6, 4, v4
	v_add_u32_e32 v3, 0x2000, v6
	v_ashrrev_i32_e32 v2, 31, v3
	v_lshrrev_b32_e32 v2, 22, v2
	v_add_u32_e32 v2, v3, v2
	v_ashrrev_i32_e32 v2, 10, v2
	v_mul_i32_i24_e32 v5, 0x400, v2
	v_sub_u32_e32 v3, v3, v5
	v_lshrrev_b32_e32 v5, 4, v3
	v_bitop3_b32 v5, v5, v3, 32 bitop3:0x6c
	v_ashrrev_i32_e32 v3, 31, v5
	v_lshrrev_b32_e32 v3, 26, v3
	v_add_u32_e32 v7, v5, v3
	v_lshlrev_b32_e32 v8, 3, v2
	v_ashrrev_i32_e32 v3, 6, v7
	v_and_b32_e32 v8, -16, v8
	v_add_u32_e32 v8, v3, v8
	v_and_b32_e32 v9, 3, v3
	s_mov_b32 s2, 0x1ffffe0
	v_lshrrev_b32_e32 v10, 2, v8
	v_lshlrev_b32_e32 v11, 1, v8
	v_and_or_b32 v9, v8, s2, v9
	v_and_b32_e32 v10, 4, v10
	v_and_b32_e32 v11, 24, v11
	v_and_b32_e32 v7, 0xc0, v7
	v_or3_b32 v9, v9, v10, v11
	v_sub_u32_e32 v5, v5, v7
	v_mov_b32_e32 v11, 1
	v_lshlrev_b32_e32 v10, 5, v2
	v_ashrrev_i16_sdwa v5, v11, sext(v5) dst_sel:DWORD dst_unused:UNUSED_PAD src0_sel:DWORD src1_sel:BYTE_0
	v_and_b32_e32 v10, 32, v10
	v_bfe_i32 v5, v5, 0, 16
	v_add_lshl_u32 v7, v10, v5, 1
	v_lshl_add_u32 v134, v9, 7, v7
	v_lshl_add_u32 v136, v8, 7, v7
	v_bfe_i32 v7, v4, 27, 1
	v_lshrrev_b32_e32 v7, 22, v7
	v_add_u32_e32 v7, v6, v7
	v_and_b32_e32 v7, 0xfffffc00, v7
	v_sub_u32_e32 v6, v6, v7
	v_lshrrev_b32_e32 v7, 4, v6
	v_bitop3_b32 v8, v7, v6, 32 bitop3:0x6c
	v_ashrrev_i32_e32 v7, 31, v4
	v_lshrrev_b32_e32 v7, 26, v7
	s_ashr_i32 s12, s3, 6
	v_ashrrev_i32_e32 v6, 31, v6
	v_add_u32_e32 v7, v4, v7
	s_ashr_i32 s14, s3, 8
	s_lshl_b32 s38, s12, 10
	v_lshrrev_b32_e32 v6, 26, v6
	v_ashrrev_i32_e32 v7, 6, v7
	s_add_u32 s39, s94, 0xa200000
	v_add_u32_e32 v6, v8, v6
	v_lshlrev_b32_e32 v9, 3, v7
	v_readlane_b32 s6, v251, 48
	s_addc_u32 s40, s95, 0
	v_ashrrev_i32_e32 v6, 6, v6
	v_and_b32_e32 v9, -16, v9
	v_readlane_b32 s7, v251, 49
	v_add_u32_e32 v9, v6, v9
	v_and_b32_e32 v10, 3, v6
	s_movk_i32 s41, 0x55
	s_and_b64 s[6:7], s[6:7], exec
	v_and_or_b32 v10, v9, s2, v10
	s_cselect_b32 s2, s41, 0x54
	v_readlane_b32 s6, v251, 47
	s_mul_i32 s2, s6, s2
	v_readlane_b32 s6, v251, 46
	s_add_i32 s2, s2, s6
	s_mul_hi_i32 s6, s2, 0x30c30c31
	s_lshr_b32 s7, s6, 31
	s_ashr_i32 s6, s6, 4
	s_add_i32 s6, s6, s7
	s_lshl_b32 s7, s6, 2
	s_mulk_i32 s6, 0x54
	s_sub_i32 s6, s2, s6
	s_bfe_i32 s2, s6, 0x80000
	s_bfe_u32 s2, s2, 0x2000d
	s_add_i32 s10, s6, s2
	s_bfe_i32 s2, s10, 0x80000
	s_and_b32 s10, s10, 0xfc
	v_lshrrev_b32_e32 v12, 2, v9
	v_lshlrev_b32_e32 v13, 1, v9
	s_sub_i32 s6, s6, s10
	v_and_b32_e32 v12, 4, v12
	v_and_b32_e32 v13, 24, v13
	s_sext_i32_i16 s2, s2
	s_sext_i32_i8 s6, s6
	v_or3_b32 v10, v10, v12, v13
	v_mul_i32_i24_e32 v13, 64, v6
	s_lshr_b32 s2, s2, 2
	s_add_i32 s6, s7, s6
	v_sub_u32_e32 v8, v8, v13
	s_ashr_i32 s7, s6, 31
	s_bfe_i64 s[16:17], s[2:3], 0x100000
	v_lshlrev_b32_e32 v12, 5, v7
	v_ashrrev_i16_sdwa v8, v11, sext(v8) dst_sel:DWORD dst_unused:UNUSED_PAD src0_sel:DWORD src1_sel:BYTE_0
	s_lshl_b64 s[10:11], s[6:7], 21
	s_lshl_b64 s[16:17], s[16:17], 21
	v_and_b32_e32 v12, 32, v12
	v_bfe_i32 v8, v8, 0, 16
	s_add_u32 s30, s39, s16
	v_add_lshl_u32 v11, v12, v8, 1
	s_addc_u32 s31, s40, s17
	s_add_i32 s42, s38, 0
	v_lshl_add_u32 v138, v10, 7, v11
	s_add_i32 m0, s42, 0x10000
	v_lshl_add_u32 v140, v9, 7, v11
	global_load_lds_dwordx4 v138, s[30:31]
	s_add_i32 m0, s42, 0x12000
	s_add_u32 s16, s30, 0x100000
	global_load_lds_dwordx4 v134, s[30:31]
	s_addc_u32 s17, s31, 0
	s_add_i32 m0, s42, 0x14000
	v_mov_b32_e32 v139, 0
	global_load_lds_dwordx4 v138, s[16:17]
	s_add_i32 m0, s42, 0x16000
	s_mov_b32 s7, 0
	global_load_lds_dwordx4 v134, s[16:17]
	v_readlane_b32 s16, v251, 17
	v_readlane_b32 s17, v251, 18
	s_add_u32 s26, s16, s10
	s_addc_u32 s27, s17, s11
	s_add_i32 s43, s42, 0x2000
	s_mov_b32 m0, s42
	s_add_u32 s10, s26, 0x100000
	global_load_lds_dwordx4 v140, s[26:27]
	s_mov_b32 m0, s43
	s_addc_u32 s11, s27, 0
	s_add_i32 s46, s42, 0x4000
	global_load_lds_dwordx4 v136, s[26:27]
	s_mov_b32 m0, s46
	s_add_i32 s47, s42, 0x6000
	global_load_lds_dwordx4 v140, s[10:11]
	s_mov_b32 m0, s47
	s_cmp_eq_u32 s14, 1
	global_load_lds_dwordx4 v136, s[10:11]
	v_mov_b32_e32 v135, v139
	v_mov_b32_e32 v141, v139
	v_mov_b32_e32 v137, v139
	s_cselect_b64 s[10:11], -1, 0
	s_cmp_lg_u32 s14, 1
	s_cbranch_scc1 .LBB0_530
	s_barrier
	s_setprio 1

.LBB0_676:
	s_setprio 0
	v_readlane_b32 s4, v251, 8
	s_cmp_lt_i32 s4, 7
	s_cselect_b64 s[0:1], -1, 0
	s_and_b64 s[2:3], s[0:1], s[2:3]
	s_xor_b64 s[2:3], s[2:3], -1
	v_readlane_b32 s5, v251, 9
	s_cmpk_gt_i32 s81, 0x2ff
	s_cselect_b64 s[4:5], -1, 0
	v_mov_b32_e32 v1, v0
	s_or_b64 s[2:3], s[4:5], s[2:3]
	s_and_b64 vcc, exec, s[2:3]
	v_mbcnt_lo_u32_b32 v1, -1, 0
	v_readlane_b32 s6, v251, 10
	v_readlane_b32 s7, v251, 11
	s_cbranch_vccnz .LBB0_876
	s_add_u32 s21, s94, 0x44200000
	s_addc_u32 s42, s95, 0
	s_add_u32 s43, s94, 0x4a200000
	s_addc_u32 s46, s95, 0
	s_ashr_i32 s2, s81, 8
	s_cmp_eq_u32 s2, 1
	s_cselect_b32 s3, 2, 4
	s_cselect_b32 s4, 4, 16
	s_cmpk_lt_u32 s81, 0x100
	s_cselect_b32 s6, 0, s3
	s_cselect_b32 s47, 1, s4
	s_lshr_b32 s3, 32, s6
	s_add_i32 s3, s3, -1
	s_bfe_u32 s7, s81, 0x50003
	s_and_b32 s18, s3, s7
	s_lshl_b32 s58, s18, 8
	s_add_i32 s3, s58, 0xffffff80
	s_cmp_lg_u32 s18, 0
	s_cselect_b32 s20, s3, 0
	s_ashr_i32 s3, s2, 31
	s_lshl_b32 s60, s47, 3
	s_lshl_b32 s59, s47, 10
	s_lshl_b64 s[4:5], s[2:3], 18
	s_add_u32 s4, s43, s4
	s_addc_u32 s5, s46, s5
	s_lshl_b32 s10, s18, s6
	s_sub_i32 s11, 5, s6
	s_lshl_b32 s10, s10, 8
	s_lshr_b32 s7, s7, s11
	s_or_b32 s12, s10, s7
	s_lshl_b32 s10, s12, 5
	s_add_u32 s4, s4, s10
	s_addc_u32 s5, s5, 0
	s_lshl_b32 s10, s33, 2
	s_add_u32 s10, s4, s10
	s_addc_u32 s11, s5, 0
	s_lshl_b64 s[4:5], s[2:3], 24
	s_add_u32 s3, s21, s4
	s_addc_u32 s4, s42, s5
	s_lshl_b32 s5, s12, 11
	s_add_u32 s3, s3, s5
	s_addc_u32 s4, s4, 0
	s_lshl_b32 s5, s33, 8
	s_add_u32 s12, s3, s5
	s_addc_u32 s13, s4, 0
	s_lshl_b32 s2, s2, 3
	s_or_b32 s2, s2, s33
	s_add_i32 s4, s2, 48
	s_ashr_i32 s5, s4, 31
	s_lshl_b64 s[4:5], s[4:5], 21
	v_readlane_b32 s19, v251, 44
	s_add_u32 s3, s19, s4
	v_readlane_b32 s22, v251, 45
	s_addc_u32 s4, s22, s5
	s_sub_i32 s5, 13, s6
	s_lshl_b32 s5, s7, s5
	s_lshl_b32 s6, s5, 7
	s_lshl_b32 s7, s5, 8
	s_add_u32 s14, s3, s7
	s_addc_u32 s15, s4, 0
	s_add_i32 s4, s2, 24
	s_ashr_i32 s5, s4, 31
	s_lshl_b64 s[4:5], s[4:5], 21
	s_add_u32 s3, s19, s4
	s_addc_u32 s4, s22, s5
	s_add_u32 s16, s3, s7
	s_addc_u32 s17, s4, 0
	s_ashr_i32 s3, s2, 31
	s_lshl_b64 s[2:3], s[2:3], 21
	s_add_u32 s2, s19, s2
	s_addc_u32 s3, s22, s3
	s_lshl_b32 s4, s18, 15
	s_add_i32 s4, s4, s6
	s_lshl_b32 s4, s4, 1
	s_waitcnt vmcnt(0)
	v_mov_b32_e32 v10, v0
	s_add_u32 s18, s2, s4
	s_addc_u32 s19, s3, 0
	v_readfirstlane_b32 s2, v10
	s_ashr_i32 s2, s2, 1
	s_movk_i32 s3, 0xffe0
	v_mov_b32_e32 v2, s2
	v_bfi_b32 v2, s3, v2, v10
	v_ashrrev_i32_e32 v3, 31, v2
	v_lshlrev_b64 v[2:3], 8, v[2:3]
	v_lshrrev_b32_e32 v4, 1, v10
	v_lshl_add_u64 v[2:3], s[18:19], 0, v[2:3]
	v_and_b32_e32 v198, 16, v4
	v_mov_b32_e32 v199, 0
	v_lshl_add_u64 v[2:3], v[2:3], 0, v[198:199]
	v_ashrrev_i32_e32 v11, 4, v10
	global_load_dwordx4 v[174:177], v[2:3], off
	global_load_dwordx4 v[170:173], v[2:3], off offset:32
	global_load_dwordx4 v[166:169], v[2:3], off offset:64
	global_load_dwordx4 v[162:165], v[2:3], off offset:96
	global_load_dwordx4 v[158:161], v[2:3], off offset:128
	global_load_dwordx4 v[154:157], v[2:3], off offset:160
	global_load_dwordx4 v[150:153], v[2:3], off offset:192
	global_load_dwordx4 v[146:149], v[2:3], off offset:224
	v_add_u32_e32 v2, s20, v11
	v_ashrrev_i32_e32 v3, 31, v2
	v_lshlrev_b32_e32 v12, 4, v10
	v_lshlrev_b64 v[2:3], 8, v[2:3]
	s_mov_b64 s[2:3], 0x2000
	v_and_b32_e32 v198, 0xf0, v12
	v_lshl_add_u64 v[4:5], s[14:15], 0, v[2:3]
	v_lshl_add_u64 v[6:7], v[2:3], 0, s[2:3]
	v_lshl_add_u64 v[2:3], s[16:17], 0, v[2:3]
	v_lshl_add_u64 v[2:3], v[2:3], 0, v[198:199]
	v_lshl_add_u64 v[8:9], s[16:17], 0, v[6:7]
	v_lshl_add_u64 v[8:9], v[8:9], 0, v[198:199]
	global_load_dwordx4 v[122:125], v[2:3], off
	global_load_dwordx4 v[126:129], v[8:9], off
	v_lshl_add_u64 v[2:3], v[4:5], 0, v[198:199]
	v_lshl_add_u64 v[4:5], s[14:15], 0, v[6:7]
	v_lshl_add_u64 v[4:5], v[4:5], 0, v[198:199]
	global_load_dwordx4 v[114:117], v[2:3], off
	global_load_dwordx4 v[118:121], v[4:5], off
	s_movk_i32 s2, 0xf0
	v_and_b32_e32 v3, 0x70, v10
	s_waitcnt vmcnt(0)
	v_lshlrev_b32_e32 v4, 8, v11
	v_bitop3_b32 v3, v12, v3, s2 bitop3:0x6c
	s_movk_i32 s33, 0x70
	s_movk_i32 s61, 0x60
	s_movk_i32 s62, 0x81
	s_movk_i32 s63, 0xff7e
	s_mov_b32 s64, 0x41000000
	s_mov_b32 s20, 0x3e0293ee
	v_mbcnt_hi_u32_b32 v206, -1, v1
	v_mov_b32_e32 v2, 0xff800000
	v_mov_b32_e32 v207, 0xf149f2ca
	v_mov_b32_e32 v208, 0x41b17218
	v_add3_u32 v3, 0, v4, v3
	s_mov_b32 s65, s81
	s_waitcnt vmcnt(0)
	ds_write_b128 v3, v[122:125] offset:32768
	ds_write_b128 v3, v[126:129] offset:40960
	s_waitcnt lgkmcnt(0)
	s_barrier
	s_branch .LBB0_679

.LBB0_987:
	v_readlane_b32 s0, v251, 8
	v_readlane_b32 s1, v251, 9
	s_mov_b64 s[4:5], s[0:1]
	s_cmp_lt_i32 s4, 10
	v_readlane_b32 s2, v251, 10
	v_readlane_b32 s3, v251, 11
	s_cselect_b64 s[0:1], -1, 0
	s_cmp_gt_i32 s5, 9
	s_cselect_b64 s[2:3], -1, 0
	s_and_b64 s[2:3], s[0:1], s[2:3]
	s_cmpk_lt_i32 s81, 0x200
	v_mov_b32_e32 v2, v0
	s_cselect_b64 s[4:5], -1, 0
	v_readlane_b32 s6, v251, 47
	v_cndmask_b32_e64 v2, 0, 1, s[4:5]
	s_lshl_b32 s33, s6, 6
	s_mul_i32 s58, s6, 0x41
	s_andn2_b64 vcc, exec, s[2:3]
	v_cmp_ne_u32_e64 s[2:3], 1, v2
	s_cbranch_vccnz .LBB0_1018
	v_mov_b32_e32 v3, v0
	s_and_b64 vcc, exec, s[2:3]
	v_readfirstlane_b32 s4, v3
	s_cbranch_vccnz .LBB0_1018
	s_waitcnt vmcnt(0)
	v_lshlrev_b32_e32 v6, 4, v3
	v_add_u32_e32 v4, 0x2000, v6
	v_ashrrev_i32_e32 v2, 31, v4
	v_lshrrev_b32_e32 v2, 22, v2
	v_add_u32_e32 v2, v4, v2
	v_ashrrev_i32_e32 v2, 10, v2
	v_mul_i32_i24_e32 v5, 0x400, v2
	v_sub_u32_e32 v4, v4, v5
	v_lshrrev_b32_e32 v5, 4, v4
	v_bitop3_b32 v5, v5, v4, 32 bitop3:0x6c
	v_ashrrev_i32_e32 v4, 31, v5
	v_lshrrev_b32_e32 v4, 26, v4
	v_add_u32_e32 v7, v5, v4
	v_lshlrev_b32_e32 v8, 3, v2
	v_ashrrev_i32_e32 v4, 6, v7
	v_and_b32_e32 v8, -16, v8
	v_add_u32_e32 v8, v4, v8
	v_and_b32_e32 v9, 3, v4
	s_mov_b32 s7, 0x1ffffe0
	v_lshrrev_b32_e32 v10, 2, v8
	v_lshlrev_b32_e32 v11, 1, v8
	v_and_or_b32 v9, v8, s7, v9
	v_and_b32_e32 v10, 4, v10
	v_and_b32_e32 v11, 24, v11
	v_and_b32_e32 v7, 0xc0, v7
	v_or3_b32 v9, v9, v10, v11
	v_sub_u32_e32 v5, v5, v7
	v_mov_b32_e32 v11, 1
	v_lshlrev_b32_e32 v10, 5, v2
	v_ashrrev_i16_sdwa v5, v11, sext(v5) dst_sel:DWORD dst_unused:UNUSED_PAD src0_sel:DWORD src1_sel:BYTE_0
	v_and_b32_e32 v10, 32, v10
	v_bfe_i32 v5, v5, 0, 16
	v_add_lshl_u32 v7, v10, v5, 1
	v_lshl_add_u32 v178, v9, 7, v7
	v_lshl_add_u32 v180, v8, 7, v7
	v_bfe_i32 v7, v3, 27, 1
	v_lshrrev_b32_e32 v7, 22, v7
	v_add_u32_e32 v7, v6, v7
	v_and_b32_e32 v7, 0xfffffc00, v7
	v_sub_u32_e32 v6, v6, v7
	v_lshrrev_b32_e32 v7, 4, v6
	v_bitop3_b32 v8, v7, v6, 32 bitop3:0x6c
	v_ashrrev_i32_e32 v7, 31, v3
	v_lshrrev_b32_e32 v7, 26, v7
	v_ashrrev_i32_e32 v6, 31, v6
	v_add_u32_e32 v7, v3, v7
	v_lshrrev_b32_e32 v6, 26, v6
	v_ashrrev_i32_e32 v7, 6, v7
	s_ashr_i32 s6, s4, 6
	v_add_u32_e32 v6, v8, v6
	v_lshlrev_b32_e32 v9, 3, v7
	v_readlane_b32 s12, v251, 48
	s_ashr_i32 s5, s4, 8
	s_lshl_b32 s36, s6, 10
	v_ashrrev_i32_e32 v6, 6, v6
	v_and_b32_e32 v9, -16, v9
	v_readlane_b32 s13, v251, 49
	v_add_u32_e32 v9, v6, v9
	v_and_b32_e32 v10, 3, v6
	s_and_b64 s[12:13], s[12:13], exec
	v_and_or_b32 v10, v9, s7, v10
	s_cselect_b32 s7, s58, s33
	v_readlane_b32 s12, v251, 46
	s_add_i32 s7, s7, s12
	s_ashr_i32 s12, s7, 31
	s_lshr_b32 s12, s12, 26
	s_add_i32 s12, s7, s12
	s_ashr_i32 s13, s12, 6
	s_and_b32 s12, s12, 0xffc0
	s_sub_i32 s12, s7, s12
	s_bfe_i32 s7, s12, 0x80000
	s_bfe_u32 s7, s7, 0x2000d
	s_add_i32 s14, s12, s7
	v_lshrrev_b32_e32 v12, 2, v9
	v_lshlrev_b32_e32 v13, 1, v9
	s_bfe_i32 s7, s14, 0x80000
	s_and_b32 s14, s14, 0xfc
	v_and_b32_e32 v12, 4, v12
	v_and_b32_e32 v13, 24, v13
	s_sub_i32 s12, s12, s14
	v_or3_b32 v10, v10, v12, v13
	v_mul_i32_i24_e32 v13, 64, v6
	s_lshl_b32 s13, s13, 2
	s_sext_i32_i16 s15, s7
	s_sext_i32_i8 s12, s12
	v_sub_u32_e32 v8, v8, v13
	s_add_i32 s65, s13, s12
	s_ashr_i32 s12, s15, 2
	v_lshlrev_b32_e32 v12, 5, v7
	v_ashrrev_i16_sdwa v8, v11, sext(v8) dst_sel:DWORD dst_unused:UNUSED_PAD src0_sel:DWORD src1_sel:BYTE_0
	s_lshr_b32 s7, s15, 2
	s_mul_hi_i32 s13, s12, 0x180000
	s_mul_i32 s12, s12, 0x180000
	v_and_b32_e32 v12, 32, v12
	v_bfe_i32 v8, v8, 0, 16
	s_add_u32 s26, s8, s12
	v_add_lshl_u32 v11, v12, v8, 1
	s_addc_u32 s27, s9, s13
	s_add_i32 s37, s36, 0
	v_lshl_add_u32 v182, v10, 7, v11
	s_add_i32 m0, s37, 0x10000
	s_mul_i32 s16, s65, 0x180000
	global_load_lds_dwordx4 v182, s[26:27]
	s_add_i32 m0, s37, 0x12000
	s_add_u32 s12, s26, 0xc0000
	global_load_lds_dwordx4 v178, s[26:27]
	s_addc_u32 s13, s27, 0
	s_add_i32 m0, s37, 0x14000
	s_mul_hi_i32 s14, s65, 0x180000
	global_load_lds_dwordx4 v182, s[12:13]
	s_add_i32 m0, s37, 0x16000
	s_add_u32 s24, s10, s16
	s_addc_u32 s25, s11, s14
	s_add_i32 s38, s37, 0x2000
	v_lshl_add_u32 v184, v9, 7, v11
	global_load_lds_dwordx4 v178, s[12:13]
	s_mov_b32 m0, s37
	s_add_u32 s12, s24, 0xc0000
	global_load_lds_dwordx4 v184, s[24:25]
	s_mov_b32 m0, s38
	s_addc_u32 s13, s25, 0
	s_add_i32 s39, s37, 0x4000
	global_load_lds_dwordx4 v180, s[24:25]
	s_mov_b32 m0, s39
	s_add_i32 s40, s37, 0x6000
	global_load_lds_dwordx4 v184, s[12:13]
	s_mov_b32 m0, s40
	v_mov_b32_e32 v187, 0
	global_load_lds_dwordx4 v180, s[12:13]
	s_cmp_eq_u32 s5, 1
	s_mov_b32 s13, 0
	v_mov_b32_e32 v183, v187
	v_mov_b32_e32 v179, v187
	v_mov_b32_e32 v185, v187
	s_cselect_b64 s[14:15], -1, 0
	s_cmp_lg_u32 s5, 1
	v_mov_b32_e32 v181, v187
	s_cbranch_scc1 .LBB0_991
	s_barrier
	s_setprio 1

.LBB0_1072:
	s_setprio 0
	v_readlane_b32 s8, v251, 8
	s_cmp_lt_i32 s8, 11
	v_readlane_b32 s9, v251, 9
	s_cselect_b64 s[0:1], -1, 0
	s_add_u32 s8, s94, 0x37e00000
	s_addc_u32 s9, s95, 0
	s_add_u32 s14, s94, 0x61400000
	s_addc_u32 s15, s95, 0
	s_add_u32 s12, s94, 0x61800000
	v_readlane_b32 s10, v251, 10
	s_addc_u32 s13, s95, 0
	v_readlane_b32 s11, v251, 11
	s_add_u32 s10, s94, 0x56400000
	s_addc_u32 s11, s95, 0
	s_and_b64 s[4:5], s[0:1], s[4:5]
	v_mov_b32_e32 v2, v0
	s_andn2_b64 vcc, exec, s[4:5]
	s_cbranch_vccnz .LBB0_1147
	v_mov_b32_e32 v2, v0
	s_and_b64 vcc, exec, s[2:3]
	v_readfirstlane_b32 s4, v2
	s_cbranch_vccnz .LBB0_1075
	v_readlane_b32 s6, v251, 48
	v_readlane_b32 s7, v251, 49
	s_and_b64 s[6:7], s[6:7], exec
	s_cselect_b32 s5, s58, s33
	v_readlane_b32 s6, v251, 46
	s_add_i32 s5, s5, s6
	s_ashr_i32 s6, s5, 31
	s_lshr_b32 s6, s6, 26
	s_add_i32 s6, s5, s6
	s_ashr_i32 s7, s6, 6
	s_and_b32 s6, s6, 0xffc0
	s_sub_i32 s5, s5, s6
	s_bfe_i32 s6, s5, 0x80000
	s_bfe_u32 s6, s6, 0x2000d
	s_add_i32 s6, s5, s6
	s_bfe_i32 s16, s6, 0x80000
	s_and_b32 s6, s6, 0xfc
	s_sub_i32 s5, s5, s6
	s_lshl_b32 s7, s7, 2
	s_sext_i32_i16 s16, s16
	s_sext_i32_i8 s5, s5
	s_add_i32 s34, s7, s5
	s_ashr_i32 s16, s16, 2
.LBB0_1075:
	s_and_b64 vcc, exec, s[2:3]
	s_cbranch_vccnz .LBB0_1111
	v_bfe_i32 v4, v2, 27, 1
	s_waitcnt vmcnt(0)
	v_lshlrev_b32_e32 v6, 4, v2
	v_lshrrev_b32_e32 v4, 22, v4
	v_add_u32_e32 v4, v6, v4
	v_and_b32_e32 v4, 0xfffffc00, v4
	v_sub_u32_e32 v4, v6, v4
	v_lshrrev_b32_e32 v5, 4, v4
	v_bitop3_b32 v5, v5, v4, 32 bitop3:0x6c
	v_ashrrev_i32_e32 v4, 31, v4
	v_lshrrev_b32_e32 v4, 26, v4
	v_ashrrev_i32_e32 v3, 31, v2
	v_add_u32_e32 v4, v5, v4
	v_lshrrev_b32_e32 v3, 26, v3
	v_ashrrev_i32_e32 v4, 6, v4
	v_add_u32_e32 v3, v2, v3
	v_mul_i32_i24_e32 v9, 64, v4
	v_ashrrev_i32_e32 v3, 6, v3
	v_sub_u32_e32 v5, v5, v9
	v_mov_b32_e32 v9, 1
	v_lshlrev_b32_e32 v7, 3, v3
	v_lshlrev_b32_e32 v8, 5, v3
	v_ashrrev_i16_sdwa v5, v9, sext(v5) dst_sel:DWORD dst_unused:UNUSED_PAD src0_sel:DWORD src1_sel:BYTE_0
	v_and_b32_e32 v7, -16, v7
	v_and_b32_e32 v8, 32, v8
	v_bfe_i32 v5, v5, 0, 16
	v_add_u32_e32 v7, v4, v7
	v_and_b32_e32 v12, 3, v4
	s_mov_b32 s6, 0x1ffffe0
	v_add_lshl_u32 v8, v8, v5, 1
	v_lshlrev_b32_e32 v10, 1, v7
	v_lshrrev_b32_e32 v11, 2, v7
	v_and_or_b32 v12, v7, s6, v12
	v_lshl_add_u32 v178, v7, 7, v8
	v_add_u32_e32 v7, 0x2000, v6
	v_ashrrev_i32_e32 v6, 31, v7
	v_lshrrev_b32_e32 v6, 22, v6
	v_and_b32_e32 v10, 24, v10
	v_and_b32_e32 v11, 4, v11
	v_add_u32_e32 v6, v7, v6
	v_or3_b32 v10, v12, v11, v10
	v_ashrrev_i32_e32 v6, 10, v6
	v_lshl_add_u32 v180, v10, 7, v8
	v_mul_i32_i24_e32 v8, 0x400, v6
	v_sub_u32_e32 v7, v7, v8
	v_lshrrev_b32_e32 v8, 4, v7
	v_bitop3_b32 v8, v8, v7, 32 bitop3:0x6c
	v_lshlrev_b32_e32 v7, 3, v6
	v_and_b32_e32 v10, -16, v7
	v_ashrrev_i32_e32 v7, 31, v8
	v_lshrrev_b32_e32 v7, 26, v7
	v_add_u32_e32 v11, v8, v7
	v_ashrrev_i32_e32 v7, 6, v11
	s_ashr_i32 s5, s4, 6
	v_add_u32_e32 v10, v7, v10
	v_and_b32_e32 v13, 3, v7
	s_ashr_i32 s35, s34, 31
	s_ashr_i32 s17, s16, 31
	v_and_b32_e32 v11, 0xc0, v11
	v_and_or_b32 v13, v10, s6, v13
	s_ashr_i32 s6, s4, 8
	s_lshl_b32 s46, s5, 10
	s_lshl_b64 s[18:19], s[34:35], 21
	s_lshl_b64 s[20:21], s[16:17], 21
	v_sub_u32_e32 v8, v8, v11
	s_add_u32 s38, s52, s20
	v_lshlrev_b32_e32 v12, 5, v6
	v_ashrrev_i16_sdwa v8, v9, sext(v8) dst_sel:DWORD dst_unused:UNUSED_PAD src0_sel:DWORD src1_sel:BYTE_0
	v_lshlrev_b32_e32 v9, 1, v10
	v_lshrrev_b32_e32 v11, 2, v10
	s_addc_u32 s39, s53, s21
	s_add_i32 s47, s46, 0
	v_and_b32_e32 v12, 32, v12
	v_bfe_i32 v8, v8, 0, 16
	v_and_b32_e32 v9, 24, v9
	v_and_b32_e32 v11, 4, v11
	s_add_i32 m0, s47, 0x10000
	v_or3_b32 v9, v13, v11, v9
	v_add_lshl_u32 v11, v12, v8, 1
	global_load_lds_dwordx4 v180, s[38:39]
	s_add_i32 m0, s47, 0x12000
	v_lshl_add_u32 v184, v9, 7, v11
	s_add_u32 s20, s38, 0x100000
	global_load_lds_dwordx4 v184, s[38:39]
	s_addc_u32 s21, s39, 0
	s_add_i32 m0, s47, 0x14000
	v_lshl_add_u32 v182, v10, 7, v11
	global_load_lds_dwordx4 v180, s[20:21]
	s_add_i32 m0, s47, 0x16000
	s_add_u32 s36, s28, s18
	s_addc_u32 s37, s29, s19
	s_add_i32 s59, s47, 0x2000
	global_load_lds_dwordx4 v184, s[20:21]
	s_mov_b32 m0, s47
	s_add_u32 s18, s36, 0x100000
	global_load_lds_dwordx4 v178, s[36:37]
	s_mov_b32 m0, s59
	s_addc_u32 s19, s37, 0
	s_add_i32 s60, s47, 0x4000
	global_load_lds_dwordx4 v182, s[36:37]
	s_mov_b32 m0, s60
	s_add_i32 s61, s47, 0x6000
	global_load_lds_dwordx4 v178, s[18:19]
	s_mov_b32 m0, s61
	v_mov_b32_e32 v187, 0
	global_load_lds_dwordx4 v182, s[18:19]
	s_cmp_eq_u32 s6, 1
	s_mov_b32 s17, 0
	v_mov_b32_e32 v181, v187
	v_mov_b32_e32 v185, v187
	v_mov_b32_e32 v179, v187
	s_cselect_b64 s[18:19], -1, 0
	s_cmp_lg_u32 s6, 1
	v_mov_b32_e32 v183, v187
	s_cbranch_scc1 .LBB0_1078
	s_barrier
	s_setprio 1

.LBB0_1113:
	s_and_b64 vcc, exec, s[2:3]
	s_cbranch_vccnz .LBB0_1147
	v_bfe_i32 v5, v2, 27, 1
	s_waitcnt lgkmcnt(0)
	v_lshlrev_b32_e32 v3, 4, v2
	v_lshrrev_b32_e32 v5, 22, v5
	v_add_u32_e32 v5, v3, v5
	v_and_b32_e32 v5, 0xfffffc00, v5
	v_sub_u32_e32 v5, v3, v5
	v_ashrrev_i32_e32 v4, 31, v2
	s_waitcnt vmcnt(0)
	v_lshrrev_b32_e32 v6, 4, v5
	v_lshrrev_b32_e32 v4, 26, v4
	v_bitop3_b32 v6, v6, v5, 32 bitop3:0x6c
	v_ashrrev_i32_e32 v5, 31, v5
	v_add_u32_e32 v4, v2, v4
	v_lshrrev_b32_e32 v5, 26, v5
	v_ashrrev_i32_e32 v4, 6, v4
	v_add_u32_e32 v5, v6, v5
	v_lshlrev_b32_e32 v7, 3, v4
	v_ashrrev_i32_e32 v5, 6, v5
	v_and_b32_e32 v7, -16, v7
	v_mul_i32_i24_e32 v8, 64, v5
	v_add_u32_e32 v7, v5, v7
	v_sub_u32_e32 v6, v6, v8
	v_mov_b32_e32 v8, 1
	v_lshlrev_b32_e32 v4, 5, v4
	v_ashrrev_i16_sdwa v6, v8, sext(v6) dst_sel:DWORD dst_unused:UNUSED_PAD src0_sel:DWORD src1_sel:BYTE_0
	v_lshlrev_b32_e32 v9, 1, v7
	v_lshrrev_b32_e32 v10, 2, v7
	v_and_b32_e32 v5, 3, v5
	s_mov_b32 s6, 0x1ffffe0
	v_and_b32_e32 v4, 32, v4
	v_bfe_i32 v6, v6, 0, 16
	v_and_b32_e32 v9, 24, v9
	v_and_b32_e32 v10, 4, v10
	v_and_or_b32 v5, v7, s6, v5
	v_or3_b32 v5, v5, v10, v9
	v_add_lshl_u32 v4, v4, v6, 1
	v_add_u32_e32 v3, 0x2000, v3
	v_lshl_add_u32 v130, v7, 7, v4
	v_lshl_add_u32 v132, v5, 7, v4
	v_ashrrev_i32_e32 v4, 31, v3
	v_lshrrev_b32_e32 v4, 22, v4
	v_add_u32_e32 v4, v3, v4
	v_ashrrev_i32_e32 v4, 10, v4
	v_mul_i32_i24_e32 v5, 0x400, v4
	v_sub_u32_e32 v3, v3, v5
	v_lshrrev_b32_e32 v5, 4, v3
	v_bitop3_b32 v3, v5, v3, 32 bitop3:0x6c
	v_ashrrev_i32_e32 v6, 31, v3
	v_lshrrev_b32_e32 v6, 26, v6
	v_lshlrev_b32_e32 v5, 3, v4
	v_add_u32_e32 v6, v3, v6
	v_and_b32_e32 v5, -16, v5
	v_ashrrev_i32_e32 v7, 6, v6
	s_ashr_i32 s5, s4, 6
	v_add_u32_e32 v5, v7, v5
	v_and_b32_e32 v7, 3, v7
	s_ashr_i32 s35, s34, 31
	s_ashr_i32 s17, s16, 31
	v_and_b32_e32 v6, 0xc0, v6
	v_and_or_b32 v7, v5, s6, v7
	s_ashr_i32 s6, s4, 8
	s_lshl_b32 s56, s5, 10
	s_lshl_b64 s[18:19], s[34:35], 17
	s_lshl_b64 s[20:21], s[16:17], 17
	v_sub_u32_e32 v3, v3, v6
	s_add_u32 s40, s54, s20
	v_lshlrev_b32_e32 v4, 5, v4
	v_ashrrev_i16_sdwa v3, v8, sext(v3) dst_sel:DWORD dst_unused:UNUSED_PAD src0_sel:DWORD src1_sel:BYTE_0
	v_lshlrev_b32_e32 v6, 1, v5
	v_lshrrev_b32_e32 v8, 2, v5
	s_addc_u32 s41, s55, s21
	s_add_i32 s57, s56, 0
	v_and_b32_e32 v4, 32, v4
	v_bfe_i32 v3, v3, 0, 16
	v_and_b32_e32 v6, 24, v6
	v_and_b32_e32 v8, 4, v8
	s_add_i32 m0, s57, 0x10000
	v_or3_b32 v6, v7, v8, v6
	v_add_lshl_u32 v3, v4, v3, 1
	global_load_lds_dwordx4 v132, s[40:41]
	s_add_i32 m0, s57, 0x12000
	v_lshl_add_u32 v136, v6, 7, v3
	s_add_u32 s20, s40, 0x10000
	global_load_lds_dwordx4 v136, s[40:41]
	s_addc_u32 s21, s41, 0
	s_add_i32 m0, s57, 0x14000
	v_lshl_add_u32 v134, v5, 7, v3
	global_load_lds_dwordx4 v132, s[20:21]
	s_add_i32 m0, s57, 0x16000
	v_mov_b32_e32 v133, 0
	global_load_lds_dwordx4 v136, s[20:21]
	v_readlane_b32 s20, v251, 19
	v_readlane_b32 s21, v251, 20
	s_add_u32 s36, s20, s18
	s_addc_u32 s37, s21, s19
	s_add_i32 s59, s57, 0x2000
	s_mov_b32 m0, s57
	s_add_u32 s18, s36, 0x10000
	global_load_lds_dwordx4 v130, s[36:37]
	s_mov_b32 m0, s59
	s_addc_u32 s19, s37, 0
	s_add_i32 s60, s57, 0x4000
	global_load_lds_dwordx4 v134, s[36:37]
	s_mov_b32 m0, s60
	s_add_i32 s61, s57, 0x6000
	global_load_lds_dwordx4 v130, s[18:19]
	s_mov_b32 m0, s61
	s_cmp_eq_u32 s6, 1
	global_load_lds_dwordx4 v134, s[18:19]
	s_mov_b32 s17, 0
	v_mov_b32_e32 v137, v133
	v_mov_b32_e32 v131, v133
	s_cselect_b64 s[18:19], -1, 0
	s_cmp_lg_u32 s6, 1
	v_mov_b32_e32 v135, v133
	s_cbranch_scc1 .LBB0_1116
	s_barrier
	s_setprio 1

.LBB0_1201:
	s_setprio 0
	v_readlane_b32 s4, v251, 8
	v_readlane_b32 s5, v251, 9
	s_cmp_lt_i32 s4, 13
	s_cselect_b64 s[0:1], -1, 0
	s_cmp_gt_i32 s5, 12
	v_mov_b32_e32 v2, v0
	s_cselect_b64 s[4:5], -1, 0
	s_and_b64 s[4:5], s[0:1], s[4:5]
	v_mov_b32_e32 v2, v0
	s_andn2_b64 vcc, exec, s[4:5]
	v_readlane_b32 s6, v251, 10
	v_readlane_b32 s7, v251, 11
	s_cbranch_vccnz .LBB0_1222
	s_waitcnt lgkmcnt(0)
	v_mov_b32_e32 v3, v0
	s_cmpk_gt_i32 s81, 0x7ff
	s_nop 0
	v_readfirstlane_b32 s5, v3
	s_cbranch_scc1 .LBB0_1222
	s_waitcnt vmcnt(0)
	v_lshlrev_b32_e32 v6, 4, v3
	v_add_u32_e32 v4, 0x2000, v6
	v_ashrrev_i32_e32 v2, 31, v4
	v_lshrrev_b32_e32 v2, 22, v2
	v_add_u32_e32 v2, v4, v2
	v_ashrrev_i32_e32 v2, 10, v2
	v_mul_i32_i24_e32 v5, 0x400, v2
	v_sub_u32_e32 v4, v4, v5
	v_lshrrev_b32_e32 v5, 4, v4
	v_bitop3_b32 v5, v5, v4, 32 bitop3:0x6c
	v_ashrrev_i32_e32 v4, 31, v5
	v_lshrrev_b32_e32 v4, 26, v4
	v_add_u32_e32 v7, v5, v4
	v_lshlrev_b32_e32 v8, 3, v2
	v_ashrrev_i32_e32 v4, 6, v7
	v_and_b32_e32 v8, -16, v8
	v_readlane_b32 s6, v251, 47
	v_add_u32_e32 v8, v4, v8
	s_lshl_b32 s4, s6, 8
	s_mul_i32 s18, s6, 0x101
	v_and_b32_e32 v9, 3, v4
	s_mov_b32 s6, 0x1ffffe0
	v_lshrrev_b32_e32 v10, 2, v8
	v_lshlrev_b32_e32 v11, 1, v8
	v_and_or_b32 v9, v8, s6, v9
	v_and_b32_e32 v10, 4, v10
	v_and_b32_e32 v11, 24, v11
	v_and_b32_e32 v7, 0xc0, v7
	v_or3_b32 v9, v9, v10, v11
	v_sub_u32_e32 v5, v5, v7
	v_mov_b32_e32 v11, 1
	v_lshlrev_b32_e32 v10, 5, v2
	v_ashrrev_i16_sdwa v5, v11, sext(v5) dst_sel:DWORD dst_unused:UNUSED_PAD src0_sel:DWORD src1_sel:BYTE_0
	v_and_b32_e32 v10, 32, v10
	v_bfe_i32 v5, v5, 0, 16
	v_add_lshl_u32 v7, v10, v5, 1
	v_lshl_add_u32 v130, v9, 7, v7
	v_lshl_add_u32 v132, v8, 7, v7
	v_bfe_i32 v7, v3, 27, 1
	v_lshrrev_b32_e32 v7, 22, v7
	v_add_u32_e32 v7, v6, v7
	v_and_b32_e32 v7, 0xfffffc00, v7
	v_sub_u32_e32 v6, v6, v7
	v_lshrrev_b32_e32 v7, 4, v6
	v_bitop3_b32 v8, v7, v6, 32 bitop3:0x6c
	v_ashrrev_i32_e32 v7, 31, v3
	v_lshrrev_b32_e32 v7, 26, v7
	v_ashrrev_i32_e32 v6, 31, v6
	v_add_u32_e32 v7, v3, v7
	v_lshrrev_b32_e32 v6, 26, v6
	v_ashrrev_i32_e32 v7, 6, v7
	v_add_u32_e32 v6, v8, v6
	v_lshlrev_b32_e32 v9, 3, v7
	v_ashrrev_i32_e32 v6, 6, v6
	v_and_b32_e32 v9, -16, v9
	v_add_u32_e32 v9, v6, v9
	v_and_b32_e32 v10, 3, v6
	s_ashr_i32 s17, s5, 6
	v_and_or_b32 v10, v9, s6, v10
	v_readlane_b32 s6, v251, 48
	s_ashr_i32 s16, s5, 8
	s_lshl_b32 s38, s17, 10
	v_readlane_b32 s7, v251, 49
	s_and_b64 s[6:7], s[6:7], exec
	s_cselect_b32 s4, s18, s4
	v_readlane_b32 s6, v251, 46
	s_add_i32 s4, s4, s6
	s_ashr_i32 s6, s4, 31
	s_lshr_b32 s6, s6, 24
	s_add_i32 s6, s4, s6
	s_ashr_i32 s7, s6, 8
	s_and_b32 s6, s6, 0xff00
	s_sub_i32 s6, s4, s6
	s_sext_i32_i16 s4, s6
	s_bfe_u32 s4, s4, 0x2001d
	s_add_i32 s18, s6, s4
	s_sext_i32_i16 s4, s18
	s_and_b32 s18, s18, 0xfffc
	v_lshrrev_b32_e32 v12, 2, v9
	v_lshlrev_b32_e32 v13, 1, v9
	s_sub_i32 s6, s6, s18
	v_and_b32_e32 v12, 4, v12
	v_and_b32_e32 v13, 24, v13
	s_lshl_b32 s7, s7, 2
	s_sext_i32_i16 s6, s6
	v_or3_b32 v10, v10, v12, v13
	v_mul_i32_i24_e32 v13, 64, v6
	s_lshr_b32 s4, s4, 2
	s_add_i32 s26, s7, s6
	v_sub_u32_e32 v8, v8, v13
	s_ashr_i32 s27, s26, 31
	s_bfe_i64 s[18:19], s[4:5], 0x100000
	v_lshlrev_b32_e32 v12, 5, v7
	v_ashrrev_i16_sdwa v8, v11, sext(v8) dst_sel:DWORD dst_unused:UNUSED_PAD src0_sel:DWORD src1_sel:BYTE_0
	s_lshl_b64 s[6:7], s[26:27], 21
	s_lshl_b64 s[18:19], s[18:19], 21
	v_and_b32_e32 v12, 32, v12
	v_bfe_i32 v8, v8, 0, 16
	s_add_u32 s30, s65, s18
	v_readlane_b32 s18, v251, 50
	v_add_lshl_u32 v11, v12, v8, 1
	s_addc_u32 s31, s18, s19
	s_add_i32 s39, s38, 0
	v_lshl_add_u32 v134, v10, 7, v11
	s_add_i32 m0, s39, 0x10000
	v_lshl_add_u32 v136, v9, 7, v11
	global_load_lds_dwordx4 v134, s[30:31]
	s_add_i32 m0, s39, 0x12000
	s_add_u32 s18, s30, 0x100000
	global_load_lds_dwordx4 v130, s[30:31]
	s_addc_u32 s19, s31, 0
	s_add_i32 m0, s39, 0x14000
	v_mov_b32_e32 v139, 0
	global_load_lds_dwordx4 v134, s[18:19]
	s_add_i32 m0, s39, 0x16000
	s_add_u32 s28, s10, s6
	s_addc_u32 s29, s11, s7
	s_add_i32 s40, s39, 0x2000
	global_load_lds_dwordx4 v130, s[18:19]
	s_mov_b32 m0, s39
	s_add_u32 s6, s28, 0x100000
	global_load_lds_dwordx4 v136, s[28:29]
	s_mov_b32 m0, s40
	s_addc_u32 s7, s29, 0
	s_add_i32 s41, s39, 0x4000
	global_load_lds_dwordx4 v132, s[28:29]
	s_mov_b32 m0, s41
	s_add_i32 s42, s39, 0x6000
	global_load_lds_dwordx4 v136, s[6:7]
	s_mov_b32 m0, s42
	s_cmp_eq_u32 s16, 1
	global_load_lds_dwordx4 v132, s[6:7]
	s_mov_b32 s43, 0
	v_mov_b32_e32 v135, v139
	v_mov_b32_e32 v131, v139
	v_mov_b32_e32 v137, v139
	s_cselect_b64 s[6:7], -1, 0
	s_cmp_lg_u32 s16, 1
	v_mov_b32_e32 v133, v139
	s_cbranch_scc1 .LBB0_1205
	s_barrier
	s_setprio 1

.LBB0_1276:
	s_setprio 0
	v_readlane_b32 s16, v251, 8
	v_readlane_b32 s17, v251, 9
	v_readlane_b32 s18, v251, 10
	s_cmp_lt_i32 s16, 14
	v_readlane_b32 s19, v251, 11
	s_cselect_b64 s[16:17], -1, 0
	s_add_u32 s18, s94, 0x61600000
	s_addc_u32 s19, s95, 0
	s_add_u32 s0, s94, 0x5a400000
	s_addc_u32 s1, s95, 0
	s_and_b64 s[4:5], s[16:17], s[4:5]
	v_mov_b32_e32 v4, v0
	s_andn2_b64 vcc, exec, s[4:5]
	s_cbranch_vccnz .LBB0_1315
	s_add_u32 s20, s94, 0x61a00000
	v_readlane_b32 s4, v251, 48
	s_addc_u32 s21, s95, 0
	v_readlane_b32 s5, v251, 49
	s_and_b64 s[4:5], s[4:5], exec
	s_cselect_b32 s4, s58, s33
	v_readlane_b32 s5, v251, 46
	s_add_i32 s4, s4, s5
	s_ashr_i32 s5, s4, 31
	s_lshr_b32 s5, s5, 26
	s_add_i32 s5, s4, s5
	s_ashr_i32 s6, s5, 6
	s_lshl_b32 s6, s6, 2
	s_sub_i32 s7, 32, s6
	s_min_i32 s7, s7, 4
	s_abs_i32 s22, s7
	v_cvt_f32_u32_e32 v2, s22
	s_sub_i32 s24, 0, s22
	s_andn2_b32 s5, s5, 63
	s_sub_i32 s4, s4, s5
	v_rcp_iflag_f32_e32 v2, v2
	s_abs_i32 s5, s4
	s_xor_b32 s23, s4, s7
	s_ashr_i32 s23, s23, 31
	v_mul_f32_e32 v2, 0x4f7ffffe, v2
	v_cvt_u32_f32_e32 v2, v2
	s_waitcnt lgkmcnt(0)
	v_ashrrev_i32_e32 v3, 1, v4
	v_and_b32_e32 v38, 1, v4
	v_lshlrev_b32_e32 v4, 7, v38
	v_readfirstlane_b32 s25, v2
	s_mul_i32 s24, s24, s25
	s_mul_hi_u32 s24, s25, s24
	s_add_i32 s25, s25, s24
	s_mul_hi_u32 s24, s5, s25
	s_mul_i32 s25, s24, s22
	s_sub_i32 s5, s5, s25
	s_add_i32 s26, s24, 1
	s_sub_i32 s25, s5, s22
	s_cmp_ge_u32 s5, s22
	s_cselect_b32 s24, s26, s24
	s_cselect_b32 s5, s25, s5
	s_add_i32 s25, s24, 1
	s_cmp_ge_u32 s5, s22
	s_cselect_b32 s5, s25, s24
	s_xor_b32 s5, s5, s23
	s_sub_i32 s36, s5, s23
	s_mul_i32 s5, s36, s7
	s_sub_i32 s4, s4, s5
	s_add_i32 s38, s6, s4
	v_lshl_add_u32 v2, s38, 8, v3
	v_ashrrev_i32_e32 v3, 31, v2
	s_waitcnt vmcnt(0)
	v_lshlrev_b64 v[6:7], 8, v[2:3]
	v_lshl_add_u64 v[6:7], s[14:15], 0, v[6:7]
	v_mov_b32_e32 v5, 0
	v_lshl_add_u64 v[4:5], v[6:7], 0, v[4:5]
	global_load_dwordx4 v[6:9], v[4:5], off
	global_load_dwordx4 v[10:13], v[4:5], off offset:16
	global_load_dwordx4 v[14:17], v[4:5], off offset:32
	global_load_dwordx4 v[18:21], v[4:5], off offset:48
	global_load_dwordx4 v[22:25], v[4:5], off offset:64
	global_load_dwordx4 v[26:29], v[4:5], off offset:80
	global_load_dwordx4 v[30:33], v[4:5], off offset:96
	global_load_dwordx4 v[34:37], v[4:5], off offset:112
	v_mbcnt_hi_u32_b32 v4, -1, v1
	v_and_b32_e32 v5, 64, v4
	v_xor_b32_e32 v39, 1, v4
	v_add_u32_e32 v5, 64, v5
	v_cmp_lt_i32_e32 vcc, v39, v5
	s_waitcnt vmcnt(6)
	v_pk_add_f32 v[8:9], v[8:9], v[12:13]
	v_pk_add_f32 v[6:7], v[6:7], v[10:11]
	s_waitcnt vmcnt(5)
	v_pk_add_f32 v[8:9], v[8:9], v[16:17]
	v_pk_add_f32 v[6:7], v[6:7], v[14:15]
	s_waitcnt vmcnt(4)
	v_pk_add_f32 v[8:9], v[8:9], v[20:21]
	v_pk_add_f32 v[6:7], v[6:7], v[18:19]
	s_waitcnt vmcnt(3)
	v_pk_add_f32 v[8:9], v[8:9], v[24:25]
	v_pk_add_f32 v[6:7], v[6:7], v[22:23]
	s_waitcnt vmcnt(2)
	v_pk_add_f32 v[8:9], v[8:9], v[28:29]
	v_pk_add_f32 v[6:7], v[6:7], v[26:27]
	s_waitcnt vmcnt(1)
	v_pk_add_f32 v[8:9], v[8:9], v[32:33]
	v_pk_add_f32 v[6:7], v[6:7], v[30:31]
	s_waitcnt vmcnt(0)
	v_pk_add_f32 v[8:9], v[8:9], v[36:37]
	v_pk_add_f32 v[6:7], v[6:7], v[34:35]
	v_cndmask_b32_e32 v39, v4, v39, vcc
	v_add_f32_e32 v6, v6, v7
	v_add_f32_e32 v7, v8, v9
	v_add_f32_e32 v6, v6, v7
	v_lshlrev_b32_e32 v7, 2, v39
	ds_bpermute_b32 v7, v7, v6
	v_cmp_eq_u32_e32 vcc, 0, v38
	s_and_saveexec_b64 s[6:7], vcc
	s_cbranch_execz .LBB0_1279
	s_waitcnt lgkmcnt(0)
	v_add_f32_e32 v6, v6, v7
	v_mov_b32_e32 v7, 0x358637bd
	v_fmac_f32_e32 v7, 0x39800000, v6
	s_mov_b32 s4, 0xf800000
	v_mul_f32_e32 v6, 0x4f800000, v7
	v_cmp_gt_f32_e32 vcc, s4, v7
	v_lshl_add_u64 v[2:3], v[2:3], 2, s[20:21]
	s_nop 0
	v_cndmask_b32_e32 v6, v7, v6, vcc
	v_sqrt_f32_e32 v7, v6
	s_nop 0
	v_add_u32_e32 v8, -1, v7
	v_fma_f32 v9, -v8, v7, v6
	v_cmp_ge_f32_e64 s[4:5], 0, v9
	v_add_u32_e32 v9, 1, v7
	s_nop 0
	v_cndmask_b32_e64 v8, v7, v8, s[4:5]
	v_fma_f32 v7, -v9, v7, v6
	v_cmp_lt_f32_e64 s[4:5], 0, v7
	s_nop 1
	v_cndmask_b32_e64 v7, v8, v9, s[4:5]
	v_mul_f32_e32 v8, 0x37800000, v7
	v_cndmask_b32_e32 v7, v7, v8, vcc
	v_mov_b32_e32 v8, 0x260
	v_cmp_class_f32_e32 vcc, v6, v8
	s_nop 1
	v_cndmask_b32_e32 v6, v7, v6, vcc
	v_div_scale_f32 v7, s[4:5], v6, v6, 1.0
	v_rcp_f32_e32 v8, v7
	s_nop 0
	v_fma_f32 v9, -v7, v8, 1.0
	v_fmac_f32_e32 v8, v9, v8
	v_div_scale_f32 v9, vcc, 1.0, v6, 1.0
	v_mul_f32_e32 v10, v9, v8
	v_fma_f32 v11, -v7, v10, v9
	v_fmac_f32_e32 v10, v11, v8
	v_fma_f32 v7, -v7, v10, v9
	v_div_fmas_f32 v7, v7, v8, v10
	v_div_fixup_f32 v6, v7, v6, 1.0
	global_store_dword v[2:3], v6, off
.LBB0_1279:
	s_or_b64 exec, exec, s[6:7]
	v_mov_b32_e32 v6, v0
	s_waitcnt lgkmcnt(0)
	s_barrier
	s_and_b64 vcc, exec, s[2:3]
	v_readfirstlane_b32 s4, v6
	s_cbranch_vccnz .LBB0_1315
	v_bfe_i32 v3, v6, 27, 1
	v_lshlrev_b32_e32 v8, 4, v6
	v_lshrrev_b32_e32 v3, 22, v3
	v_add_u32_e32 v3, v8, v3
	v_and_b32_e32 v3, 0xfffffc00, v3
	v_sub_u32_e32 v3, v8, v3
	v_lshrrev_b32_e32 v7, 4, v3
	v_bitop3_b32 v7, v7, v3, 32 bitop3:0x6c
	v_ashrrev_i32_e32 v3, 31, v3
	v_lshrrev_b32_e32 v3, 26, v3
	v_ashrrev_i32_e32 v2, 31, v6
	v_add_u32_e32 v3, v7, v3
	v_lshrrev_b32_e32 v2, 26, v2
	v_ashrrev_i32_e32 v3, 6, v3
	v_add_u32_e32 v2, v6, v2
	v_mul_i32_i24_e32 v11, 64, v3
	v_ashrrev_i32_e32 v2, 6, v2
	v_sub_u32_e32 v7, v7, v11
	v_mov_b32_e32 v11, 1
	v_lshlrev_b32_e32 v9, 3, v2
	v_lshlrev_b32_e32 v10, 5, v2
	v_ashrrev_i16_sdwa v7, v11, sext(v7) dst_sel:DWORD dst_unused:UNUSED_PAD src0_sel:DWORD src1_sel:BYTE_0
	v_and_b32_e32 v9, -16, v9
	v_and_b32_e32 v10, 32, v10
	v_bfe_i32 v7, v7, 0, 16
	v_add_u32_e32 v9, v3, v9
	v_and_b32_e32 v14, 3, v3
	s_mov_b32 s6, 0x1ffffe0
	v_add_lshl_u32 v10, v10, v7, 1
	v_lshlrev_b32_e32 v12, 1, v9
	v_lshrrev_b32_e32 v13, 2, v9
	v_and_or_b32 v14, v9, s6, v14
	v_lshl_add_u32 v154, v9, 7, v10
	v_add_u32_e32 v9, 0x2000, v8
	v_ashrrev_i32_e32 v8, 31, v9
	v_lshrrev_b32_e32 v8, 22, v8
	v_and_b32_e32 v12, 24, v12
	v_and_b32_e32 v13, 4, v13
	v_add_u32_e32 v8, v9, v8
	v_or3_b32 v12, v14, v13, v12
	v_ashrrev_i32_e32 v8, 10, v8
	v_lshl_add_u32 v156, v12, 7, v10
	v_mul_i32_i24_e32 v10, 0x400, v8
	v_sub_u32_e32 v9, v9, v10
	v_lshrrev_b32_e32 v10, 4, v9
	v_bitop3_b32 v10, v10, v9, 32 bitop3:0x6c
	v_lshlrev_b32_e32 v9, 3, v8
	v_and_b32_e32 v12, -16, v9
	v_ashrrev_i32_e32 v9, 31, v10
	v_lshrrev_b32_e32 v9, 26, v9
	v_add_u32_e32 v13, v10, v9
	v_ashrrev_i32_e32 v9, 6, v13
	s_ashr_i32 s5, s4, 6
	v_add_u32_e32 v12, v9, v12
	v_and_b32_e32 v15, 3, v9
	s_ashr_i32 s39, s38, 31
	s_ashr_i32 s37, s36, 31
	v_and_b32_e32 v13, 0xc0, v13
	v_and_or_b32 v15, v12, s6, v15
	s_ashr_i32 s6, s4, 8
	s_lshl_b32 s52, s5, 10
	s_lshl_b64 s[14:15], s[38:39], 23
	s_lshl_b64 s[22:23], s[36:37], 23
	v_sub_u32_e32 v10, v10, v13
	s_add_u32 s42, s51, s22
	v_readlane_b32 s7, v251, 62
	v_lshlrev_b32_e32 v14, 5, v8
	v_ashrrev_i16_sdwa v10, v11, sext(v10) dst_sel:DWORD dst_unused:UNUSED_PAD src0_sel:DWORD src1_sel:BYTE_0
	v_lshlrev_b32_e32 v11, 1, v12
	v_lshrrev_b32_e32 v13, 2, v12
	s_addc_u32 s43, s7, s23
	s_add_i32 s53, s52, 0
	v_and_b32_e32 v14, 32, v14
	v_bfe_i32 v10, v10, 0, 16
	v_and_b32_e32 v11, 24, v11
	v_and_b32_e32 v13, 4, v13
	s_add_i32 m0, s53, 0x10000
	v_or3_b32 v11, v15, v13, v11
	v_add_lshl_u32 v13, v14, v10, 1
	global_load_lds_dwordx4 v156, s[42:43]
	s_add_i32 m0, s53, 0x12000
	v_lshl_add_u32 v160, v11, 7, v13
	s_add_u32 s22, s42, 0x400000
	global_load_lds_dwordx4 v160, s[42:43]
	s_addc_u32 s23, s43, 0
	s_add_i32 m0, s53, 0x14000
	v_lshl_add_u32 v158, v12, 7, v13
	global_load_lds_dwordx4 v156, s[22:23]
	s_add_i32 m0, s53, 0x16000
	s_add_u32 s40, s84, s14
	s_addc_u32 s41, s85, s15
	s_add_i32 s54, s53, 0x2000
	global_load_lds_dwordx4 v160, s[22:23]
	s_mov_b32 m0, s53
	s_add_u32 s14, s40, 0x400000
	global_load_lds_dwordx4 v154, s[40:41]
	s_mov_b32 m0, s54
	s_addc_u32 s15, s41, 0
	s_add_i32 s55, s53, 0x4000
	global_load_lds_dwordx4 v158, s[40:41]
	s_mov_b32 m0, s55
	s_add_i32 s56, s53, 0x6000
	global_load_lds_dwordx4 v154, s[14:15]
	s_mov_b32 m0, s56
	v_mov_b32_e32 v163, 0
	global_load_lds_dwordx4 v158, s[14:15]
	s_cmp_eq_u32 s6, 1
	s_mov_b32 s15, 0
	v_mov_b32_e32 v157, v163
	v_mov_b32_e32 v161, v163
	v_mov_b32_e32 v155, v163
	s_cselect_b64 s[22:23], -1, 0
	s_cmp_lg_u32 s6, 1
	v_mov_b32_e32 v159, v163
	s_cbranch_scc1 .LBB0_1282
	s_barrier
	s_setprio 1

.LBB0_1369:
	s_setprio 0
	v_readlane_b32 s4, v251, 8
	v_readlane_b32 s5, v251, 9
	s_cmp_lt_i32 s4, 16
	s_cselect_b64 s[14:15], -1, 0
	s_cmp_gt_i32 s5, 15
	s_cselect_b64 s[4:5], -1, 0
	s_and_b64 s[4:5], s[14:15], s[4:5]
	v_mov_b32_e32 v2, v0
	s_waitcnt vmcnt(0)
	v_mov_b32_e32 v6, v0
	s_andn2_b64 vcc, exec, s[4:5]
	v_readlane_b32 s6, v251, 10
	v_readlane_b32 s7, v251, 11
	s_cbranch_vccnz .LBB0_1394
	s_add_u32 s16, s94, 0x61a08000
	v_readlane_b32 s4, v251, 48
	s_addc_u32 s17, s95, 0
	v_readlane_b32 s5, v251, 49
	s_and_b64 s[4:5], s[4:5], exec
	s_cselect_b32 s4, s58, s33
	v_readlane_b32 s5, v251, 46
	s_add_i32 s4, s4, s5
	s_ashr_i32 s5, s4, 31
	s_lshr_b32 s5, s5, 26
	s_add_i32 s5, s4, s5
	s_ashr_i32 s6, s5, 6
	s_lshl_b32 s6, s6, 2
	s_sub_i32 s7, 32, s6
	s_min_i32 s7, s7, 4
	s_abs_i32 s20, s7
	v_cvt_f32_u32_e32 v2, s20
	s_sub_i32 s22, 0, s20
	s_andn2_b32 s5, s5, 63
	s_sub_i32 s4, s4, s5
	v_rcp_iflag_f32_e32 v2, v2
	s_abs_i32 s5, s4
	s_xor_b32 s21, s4, s7
	s_ashr_i32 s21, s21, 31
	v_mul_f32_e32 v2, 0x4f7ffffe, v2
	v_cvt_u32_f32_e32 v2, v2
	s_waitcnt lgkmcnt(0)
	v_ashrrev_i32_e32 v3, 1, v6
	v_and_b32_e32 v42, 1, v6
	v_mov_b32_e32 v7, 0
	v_readfirstlane_b32 s23, v2
	s_mul_i32 s22, s22, s23
	s_mul_hi_u32 s22, s23, s22
	s_add_i32 s23, s23, s22
	s_mul_hi_u32 s22, s5, s23
	s_mul_i32 s23, s22, s20
	s_sub_i32 s5, s5, s23
	s_add_i32 s24, s22, 1
	s_sub_i32 s23, s5, s20
	s_cmp_ge_u32 s5, s20
	s_cselect_b32 s22, s24, s22
	s_cselect_b32 s5, s23, s5
	s_add_i32 s23, s22, 1
	s_cmp_ge_u32 s5, s20
	s_cselect_b32 s5, s23, s22
	s_xor_b32 s5, s5, s21
	s_sub_i32 s28, s5, s21
	s_mul_i32 s5, s28, s7
	s_sub_i32 s4, s4, s5
	s_add_i32 s26, s6, s4
	v_lshl_add_u32 v2, s26, 8, v3
	v_ashrrev_i32_e32 v3, 31, v2
	v_lshlrev_b64 v[4:5], 8, v[2:3]
	v_lshl_add_u64 v[8:9], s[18:19], 0, v[4:5]
	v_lshlrev_b32_e32 v6, 7, v42
	v_lshl_add_u64 v[40:41], v[8:9], 0, v[6:7]
	global_load_dwordx4 v[8:11], v[40:41], off
	global_load_dwordx4 v[12:15], v[40:41], off offset:16
	global_load_dwordx4 v[16:19], v[40:41], off offset:32
	global_load_dwordx4 v[20:23], v[40:41], off offset:48
	global_load_dwordx4 v[24:27], v[40:41], off offset:64
	global_load_dwordx4 v[28:31], v[40:41], off offset:80
	global_load_dwordx4 v[32:35], v[40:41], off offset:96
	global_load_dwordx4 v[36:39], v[40:41], off offset:112
	v_mbcnt_hi_u32_b32 v6, -1, v1
	v_and_b32_e32 v41, 64, v6
	v_xor_b32_e32 v40, 1, v6
	v_add_u32_e32 v41, 64, v41
	v_cmp_lt_i32_e32 vcc, v40, v41
	v_cmp_eq_u32_e64 s[4:5], 0, v42
	s_waitcnt vmcnt(6)
	v_pk_add_f32 v[10:11], v[10:11], v[14:15]
	v_pk_add_f32 v[8:9], v[8:9], v[12:13]
	s_waitcnt vmcnt(5)
	v_pk_add_f32 v[10:11], v[10:11], v[18:19]
	v_pk_add_f32 v[8:9], v[8:9], v[16:17]
	s_waitcnt vmcnt(4)
	v_pk_add_f32 v[10:11], v[10:11], v[22:23]
	v_pk_add_f32 v[8:9], v[8:9], v[20:21]
	s_waitcnt vmcnt(3)
	v_pk_add_f32 v[10:11], v[10:11], v[26:27]
	v_pk_add_f32 v[8:9], v[8:9], v[24:25]
	s_waitcnt vmcnt(2)
	v_pk_add_f32 v[10:11], v[10:11], v[30:31]
	v_pk_add_f32 v[8:9], v[8:9], v[28:29]
	s_waitcnt vmcnt(1)
	v_pk_add_f32 v[10:11], v[10:11], v[34:35]
	v_pk_add_f32 v[8:9], v[8:9], v[32:33]
	s_waitcnt vmcnt(0)
	v_pk_add_f32 v[10:11], v[10:11], v[38:39]
	v_pk_add_f32 v[8:9], v[8:9], v[36:37]
	v_cndmask_b32_e32 v6, v6, v40, vcc
	v_add_f32_e32 v8, v8, v9
	v_add_f32_e32 v9, v10, v11
	v_add_f32_e32 v9, v8, v9
	v_lshlrev_b32_e32 v8, 2, v6
	ds_bpermute_b32 v10, v8, v9
	v_lshlrev_b32_e32 v6, 5, v42
	s_and_saveexec_b64 s[18:19], s[4:5]
	s_cbranch_execz .LBB0_1372
	s_waitcnt lgkmcnt(0)
	v_add_f32_e32 v9, v9, v10
	v_mov_b32_e32 v10, 0x358637bd
	v_fmac_f32_e32 v10, 0x39800000, v9
	s_mov_b32 s6, 0xf800000
	v_mul_f32_e32 v9, 0x4f800000, v10
	v_cmp_gt_f32_e32 vcc, s6, v10
	s_nop 1
	v_cndmask_b32_e32 v9, v10, v9, vcc
	v_sqrt_f32_e32 v10, v9
	s_nop 0
	v_add_u32_e32 v11, -1, v10
	v_fma_f32 v12, -v11, v10, v9
	v_cmp_ge_f32_e64 s[6:7], 0, v12
	v_add_u32_e32 v12, 1, v10
	s_nop 0
	v_cndmask_b32_e64 v11, v10, v11, s[6:7]
	v_fma_f32 v10, -v12, v10, v9
	v_cmp_lt_f32_e64 s[6:7], 0, v10
	s_nop 1
	v_cndmask_b32_e64 v10, v11, v12, s[6:7]
	v_mul_f32_e32 v11, 0x37800000, v10
	v_cndmask_b32_e32 v10, v10, v11, vcc
	v_mov_b32_e32 v11, 0x260
	v_cmp_class_f32_e32 vcc, v9, v11
	s_nop 1
	v_cndmask_b32_e32 v9, v10, v9, vcc
	v_div_scale_f32 v10, s[6:7], v9, v9, 1.0
	v_rcp_f32_e32 v11, v10
	s_nop 0
	v_fma_f32 v12, -v10, v11, 1.0
	v_fmac_f32_e32 v11, v12, v11
	v_div_scale_f32 v12, vcc, 1.0, v9, 1.0
	v_mul_f32_e32 v13, v12, v11
	v_fma_f32 v14, -v10, v13, v12
	v_fmac_f32_e32 v13, v14, v11
	v_fma_f32 v10, -v10, v13, v12
	v_div_fmas_f32 v10, v10, v11, v13
	v_div_fixup_f32 v9, v10, v9, 1.0
	v_lshl_add_u64 v[10:11], v[2:3], 2, s[16:17]
	global_store_dword v[10:11], v9, off

.LBB0_1374:
	s_or_b64 exec, exec, s[12:13]
	v_mov_b32_e32 v3, v0
	s_waitcnt lgkmcnt(0)
	s_barrier
	s_and_b64 vcc, exec, s[2:3]
	v_readfirstlane_b32 s2, v3
	s_cbranch_vccnz .LBB0_1394
	v_lshlrev_b32_e32 v6, 4, v3
	v_add_u32_e32 v4, 0x2000, v6
	v_ashrrev_i32_e32 v2, 31, v4
	v_lshrrev_b32_e32 v2, 22, v2
	v_add_u32_e32 v2, v4, v2
	v_ashrrev_i32_e32 v2, 10, v2
	v_mul_i32_i24_e32 v5, 0x400, v2
	v_sub_u32_e32 v4, v4, v5
	v_lshrrev_b32_e32 v5, 4, v4
	v_bitop3_b32 v5, v5, v4, 32 bitop3:0x6c
	v_ashrrev_i32_e32 v4, 31, v5
	v_lshrrev_b32_e32 v4, 26, v4
	v_add_u32_e32 v7, v5, v4
	v_lshlrev_b32_e32 v8, 3, v2
	v_ashrrev_i32_e32 v4, 6, v7
	v_and_b32_e32 v8, -16, v8
	v_add_u32_e32 v8, v4, v8
	v_and_b32_e32 v9, 3, v4
	s_mov_b32 s4, 0x1ffffe0
	v_lshrrev_b32_e32 v10, 2, v8
	v_lshlrev_b32_e32 v11, 1, v8
	v_and_or_b32 v9, v8, s4, v9
	v_and_b32_e32 v10, 4, v10
	v_and_b32_e32 v11, 24, v11
	v_and_b32_e32 v7, 0xc0, v7
	v_or3_b32 v9, v9, v10, v11
	v_sub_u32_e32 v5, v5, v7
	v_mov_b32_e32 v11, 1
	v_lshlrev_b32_e32 v10, 5, v2
	v_ashrrev_i16_sdwa v5, v11, sext(v5) dst_sel:DWORD dst_unused:UNUSED_PAD src0_sel:DWORD src1_sel:BYTE_0
	v_and_b32_e32 v10, 32, v10
	v_bfe_i32 v5, v5, 0, 16
	v_add_lshl_u32 v7, v10, v5, 1
	v_lshl_add_u32 v162, v9, 7, v7
	v_lshl_add_u32 v164, v8, 7, v7
	v_bfe_i32 v7, v3, 27, 1
	v_lshrrev_b32_e32 v7, 22, v7
	v_add_u32_e32 v7, v6, v7
	v_and_b32_e32 v7, 0xfffffc00, v7
	v_sub_u32_e32 v6, v6, v7
	v_lshrrev_b32_e32 v7, 4, v6
	v_bitop3_b32 v8, v7, v6, 32 bitop3:0x6c
	v_ashrrev_i32_e32 v7, 31, v3
	v_lshrrev_b32_e32 v7, 26, v7
	v_ashrrev_i32_e32 v6, 31, v6
	v_add_u32_e32 v7, v3, v7
	v_lshrrev_b32_e32 v6, 26, v6
	v_ashrrev_i32_e32 v7, 6, v7
	v_add_u32_e32 v6, v8, v6
	v_lshlrev_b32_e32 v9, 3, v7
	v_ashrrev_i32_e32 v6, 6, v6
	v_and_b32_e32 v9, -16, v9
	v_add_u32_e32 v9, v6, v9
	v_and_b32_e32 v10, 3, v6
	v_lshrrev_b32_e32 v12, 2, v9
	v_lshlrev_b32_e32 v13, 1, v9
	v_and_or_b32 v10, v9, s4, v10
	v_and_b32_e32 v12, 4, v12
	v_and_b32_e32 v13, 24, v13
	v_or3_b32 v10, v10, v12, v13
	v_mul_i32_i24_e32 v13, 64, v6
	s_ashr_i32 s12, s2, 6
	v_sub_u32_e32 v8, v8, v13
	s_ashr_i32 s27, s26, 31
	s_ashr_i32 s29, s28, 31
	s_ashr_i32 s3, s2, 8
	s_lshl_b32 s33, s12, 10
	v_lshlrev_b32_e32 v12, 5, v7
	v_ashrrev_i16_sdwa v8, v11, sext(v8) dst_sel:DWORD dst_unused:UNUSED_PAD src0_sel:DWORD src1_sel:BYTE_0
	s_lshl_b64 s[4:5], s[26:27], 21
	s_lshl_b64 s[18:19], s[28:29], 21
	v_and_b32_e32 v12, 32, v12
	v_bfe_i32 v8, v8, 0, 16
	s_add_u32 s34, s48, s18
	v_add_lshl_u32 v11, v12, v8, 1
	s_addc_u32 s35, s49, s19
	s_add_i32 s40, s33, 0
	v_lshl_add_u32 v166, v10, 7, v11
	s_add_i32 m0, s40, 0x10000
	v_lshl_add_u32 v168, v9, 7, v11
	global_load_lds_dwordx4 v166, s[34:35]
	s_add_i32 m0, s40, 0x12000
	s_add_u32 s18, s34, 0x100000
	global_load_lds_dwordx4 v162, s[34:35]
	s_addc_u32 s19, s35, 0
	s_add_i32 m0, s40, 0x14000
	v_mov_b32_e32 v171, 0
	global_load_lds_dwordx4 v166, s[18:19]
	s_add_i32 m0, s40, 0x16000
	s_add_u32 s30, s0, s4
	s_addc_u32 s31, s1, s5
	s_add_i32 s41, s40, 0x2000
	global_load_lds_dwordx4 v162, s[18:19]
	s_mov_b32 m0, s40
	s_add_u32 s4, s30, 0x100000
	global_load_lds_dwordx4 v168, s[30:31]
	s_mov_b32 m0, s41
	s_addc_u32 s5, s31, 0
	s_add_i32 s42, s40, 0x4000
	global_load_lds_dwordx4 v164, s[30:31]
	s_mov_b32 m0, s42
	s_add_i32 s43, s40, 0x6000
	global_load_lds_dwordx4 v168, s[4:5]
	s_mov_b32 m0, s43
	s_cmp_eq_u32 s3, 1
	global_load_lds_dwordx4 v164, s[4:5]
	s_mov_b32 s44, 0
	v_mov_b32_e32 v167, v171
	v_mov_b32_e32 v163, v171
	v_mov_b32_e32 v169, v171
	s_cselect_b64 s[4:5], -1, 0
	s_cmp_lg_u32 s3, 1
	v_mov_b32_e32 v165, v171
	s_cbranch_scc1 .LBB0_1377
	s_barrier
	s_setprio 1

.LBB0_1448:
	s_setprio 0
	v_readlane_b32 s4, v251, 8
	s_cmp_lt_i32 s4, 17
	s_cselect_b64 s[2:3], -1, 0
	s_and_b64 s[0:1], s[2:3], s[0:1]
	v_readlane_b32 s2, v251, 24
	v_readlane_b32 s3, v251, 25
	s_and_b64 s[0:1], s[0:1], s[2:3]
	s_andn2_b64 vcc, exec, s[0:1]
	v_readlane_b32 s5, v251, 9
	v_readlane_b32 s6, v251, 10
	v_readlane_b32 s7, v251, 11
	s_cbranch_vccnz .LBB0_1451
	v_and_b32_e32 v0, 63, v0
	v_readlane_b32 s0, v251, 0
	v_mbcnt_hi_u32_b32 v1, -1, v1
	v_lshlrev_b32_e32 v2, 5, v0
	s_waitcnt lgkmcnt(0)
	v_mov_b32_e32 v3, 0
	v_readlane_b32 s1, v251, 1
	v_readlane_b32 s4, v251, 4
	v_readlane_b32 s5, v251, 5
	v_and_b32_e32 v4, 64, v1
	v_add_u32_e32 v4, 64, v4
	v_lshl_add_u64 v[16:17], s[4:5], 0, v[2:3]
	v_xor_b32_e32 v5, 1, v1
	s_mov_b64 s[0:1], 0x1000
	v_cmp_lt_i32_e32 vcc, v5, v4
	v_lshl_add_u64 v[18:19], v[16:17], 0, s[0:1]
	s_mov_b64 s[0:1], 0x1010
	v_cndmask_b32_e32 v5, v1, v5, vcc
	v_lshl_add_u64 v[20:21], v[16:17], 0, s[0:1]
	s_mov_b64 s[0:1], 0x1800
	v_lshlrev_b32_e32 v63, 2, v5
	v_xor_b32_e32 v5, 2, v1
	v_lshl_add_u64 v[22:23], v[16:17], 0, s[0:1]
	s_mov_b64 s[0:1], 0x1810
	v_cmp_lt_i32_e32 vcc, v5, v4
	v_lshl_add_u64 v[24:25], v[16:17], 0, s[0:1]
	s_mov_b64 s[0:1], 0x2000
	v_cndmask_b32_e32 v5, v1, v5, vcc
	v_lshl_add_u64 v[26:27], v[16:17], 0, s[0:1]
	s_mov_b64 s[0:1], 0x2010
	v_lshlrev_b32_e32 v80, 2, v5
	v_xor_b32_e32 v5, 4, v1
	v_lshl_add_u64 v[28:29], v[16:17], 0, s[0:1]
	s_mov_b64 s[0:1], 0x2800
	v_cmp_lt_i32_e32 vcc, v5, v4
	v_lshl_add_u64 v[30:31], v[16:17], 0, s[0:1]
	s_mov_b64 s[0:1], 0x2810
	v_cndmask_b32_e32 v5, v1, v5, vcc
	v_lshl_add_u64 v[32:33], v[16:17], 0, s[0:1]
	s_mov_b64 s[0:1], 0x3000
	v_lshlrev_b32_e32 v81, 2, v5
	v_xor_b32_e32 v5, 8, v1
	v_lshl_add_u64 v[34:35], v[16:17], 0, s[0:1]
	s_mov_b64 s[0:1], 0x3010
	v_cmp_lt_i32_e32 vcc, v5, v4
	v_lshl_add_u64 v[36:37], v[16:17], 0, s[0:1]
	s_mov_b64 s[0:1], 0x3800
	v_cndmask_b32_e32 v5, v1, v5, vcc
	v_lshl_add_u64 v[38:39], v[16:17], 0, s[0:1]
	s_mov_b64 s[0:1], 0x3810
	v_readlane_b32 s6, v251, 6
	v_lshlrev_b32_e32 v82, 2, v5
	v_xor_b32_e32 v5, 16, v1
	v_lshl_add_u64 v[40:41], v[16:17], 0, s[0:1]
	s_lshl_b64 s[0:1], s[90:91], 14
	v_readlane_b32 s7, v251, 7
	v_cmp_lt_i32_e32 vcc, v5, v4
	s_add_u32 s0, s6, s0
	v_readlane_b32 s2, v251, 2
	v_readlane_b32 s3, v251, 3
	v_cndmask_b32_e32 v5, v1, v5, vcc
	s_addc_u32 s1, s7, s1
	v_lshlrev_b32_e32 v83, 2, v5
	v_xor_b32_e32 v5, 32, v1
	v_lshl_add_u64 v[42:43], s[0:1], 0, v[2:3]
	s_lshl_b64 s[2:3], s[92:93], 14
	s_lshl_b64 s[0:1], s[90:91], 13
	v_cmp_lt_i32_e32 vcc, v5, v4
	s_add_u32 s0, s94, s0
	v_lshlrev_b32_e32 v2, 4, v0
	v_cndmask_b32_e32 v1, v1, v5, vcc
	s_addc_u32 s1, s95, s1
	v_lshlrev_b32_e32 v84, 2, v1
	v_lshl_add_u64 v[0:1], s[0:1], 0, v[2:3]
	s_mov_b64 s[0:1], 0x56400000
	v_lshl_add_u64 v[44:45], v[0:1], 0, s[0:1]
	s_lshl_b64 s[4:5], s[92:93], 13
	s_movk_i32 s6, 0x1000
	v_mov_b32_e32 v85, 0x358637bd
	s_mov_b32 s7, 0xf800000
	v_mov_b32_e32 v86, 0x260
	s_movk_i32 s8, 0x2000
	s_movk_i32 s9, 0x3000
